# grid barrier spin loops keep four polls in flight (leaders on the arrival counter, others on the XCD generation word); post-loop drains leave the polls in flight
# baseline (speedup 1.0000x reference)
; DI unsigned xb_ld(unsigned* p) { return __hip_atomic_load(p, __ATOMIC_RELAXED, __HIP_MEMORY_SCOPE_AGENT); }
; DI unsigned xb_add(unsigned* p, unsigned v) { return __hip_atomic_fetch_add(p, v, __ATOMIC_RELAXED, __HIP_MEMORY_SCOPE_AGENT); }
; #define XB_SPIN(cond, bar) do { unsigned _sp = 0; while (cond) { __builtin_amdgcn_s_sleep(1); \
;     if ((++_sp & 255u) == 0u) { if (xb_ld(&(bar)[XB_TMO])) break; if (_sp > XB_SPIN_CAP) { atomicAdd(&(bar)[XB_TMO], 1u); break; } } } } while (0)
; DI void xcd_barrier(const XcdBarrier& b) {
;     ...
;     const unsigned old = xb_add(&bar[XB_XSUB(b.x)], 1u);
;     const unsigned gen = old / nloc;
;     if (old + 1u == (gen + 1u) * nloc) {
;       __builtin_amdgcn_fence(__ATOMIC_RELEASE, "agent");
;       asm volatile("s_waitcnt vmcnt(0)" ::: "memory");
;       const unsigned og = xb_add(&bar[XB_TOP], 1u);
;       const unsigned tg = og / nx;
;       if (og + 1u == (tg + 1u) * nx) xb_add(&bar[XB_TOPGEN], 1u);
;       else XB_SPIN(xb_ld(&bar[XB_TOPGEN]) == tg, bar);
;       __builtin_amdgcn_fence(__ATOMIC_ACQUIRE, "agent");
;       xb_add(&bar[XB_XGEN(b.x)], 1u);
;       asm volatile("s_waitcnt vmcnt(0)" ::: "memory");
;     } else {
;       XB_SPIN(xb_ld(&bar[XB_XGEN(b.x)]) == gen, bar);
.LBB0_184:
	s_or_b64 exec, exec, s[14:15]
	v_cvt_f32_u32_e32 v4, v2
	s_waitcnt vmcnt(0)
	v_readfirstlane_b32 s0, v3
	buffer_inv sc1
	v_sub_u32_e32 v3, 0, v2
	v_rcp_iflag_f32_e32 v4, v4
	v_add_u32_e32 v5, s0, v1
	v_mul_f32_e32 v4, 0x4f7ffffe, v4
	v_cvt_u32_f32_e32 v4, v4
	v_mul_lo_u32 v1, v3, v4
	v_mul_hi_u32 v1, v4, v1
	v_add_u32_e32 v1, v4, v1
	v_mul_hi_u32 v1, v5, v1
	v_mul_lo_u32 v3, v1, v2
	v_sub_u32_e32 v3, v5, v3
	v_add_u32_e32 v4, 1, v1
	v_cmp_ge_u32_e32 vcc, v3, v2
	s_nop 1
	v_cndmask_b32_e32 v1, v1, v4, vcc
	v_sub_u32_e32 v4, v3, v2
	v_cndmask_b32_e32 v3, v3, v4, vcc
	v_add_u32_e32 v4, 1, v1
	v_cmp_ge_u32_e32 vcc, v3, v2
	v_add_u32_e32 v3, 1, v5
	s_nop 0
	v_cndmask_b32_e32 v1, v1, v4, vcc
	v_mul_lo_u32 v4, v2, v1
	v_add_u32_e32 v2, v4, v2
	v_cmp_ne_u32_e32 vcc, v3, v2
	s_and_saveexec_b64 s[0:1], vcc
	s_xor_b64 s[12:13], exec, s[0:1]
	s_cbranch_execz .LBB0_198
	s_waitcnt lgkmcnt(0)
	v_mov_b32_e32 v0, 0x2000
	global_load_dword v0, v0, s[10:11] offset:1024 sc1
	s_add_u32 s20, s10, 0x2400
	s_addc_u32 s21, s11, 0
	s_waitcnt vmcnt(0)
	v_cmp_eq_u32_e32 vcc, v0, v1
	v_mov_b32_e32 v231, v1
	s_and_saveexec_b64 s[14:15], vcc
	s_cbranch_execz .LBB0_197
	s_add_u32 s16, s86, 0xe7c1200
	s_addc_u32 s17, s87, 0
	s_mov_b32 s0, 1
	s_mov_b64 s[30:31], 0
	v_mov_b32_e32 v0, 0
	s_branch .LBB0_188

; DI unsigned xb_ld(unsigned* p) { return __hip_atomic_load(p, __ATOMIC_RELAXED, __HIP_MEMORY_SCOPE_AGENT); }
; #define XB_SPIN(cond, bar) do { unsigned _sp = 0; while (cond) { __builtin_amdgcn_s_sleep(1); \
;     if ((++_sp & 255u) == 0u) { if (xb_ld(&(bar)[XB_TMO])) break; if (_sp > XB_SPIN_CAP) { atomicAdd(&(bar)[XB_TMO], 1u); break; } } } } while (0)
; DI void xcd_barrier(const XcdBarrier& b) {
;     ...
;       XB_SPIN(xb_ld(&bar[XB_XGEN(b.x)]) == gen, bar);
.LBB0_192:
	global_load_dword v231, v0, s[20:21] sc1
	s_add_i32 s0, s0, 1
	s_mov_b64 s[42:43], -1
	s_waitcnt vmcnt(3)
	v_cmp_ne_u32_e32 vcc, v231, v1
	s_orn2_b64 s[36:37], vcc, exec
	s_branch .LBB0_187

; DI unsigned xb_ld(unsigned* p) { return __hip_atomic_load(p, __ATOMIC_RELAXED, __HIP_MEMORY_SCOPE_AGENT); }
; #define XB_SPIN(cond, bar) do { unsigned _sp = 0; while (cond) { __builtin_amdgcn_s_sleep(1); \
;     if ((++_sp & 255u) == 0u) { if (xb_ld(&(bar)[XB_TMO])) break; if (_sp > XB_SPIN_CAP) { atomicAdd(&(bar)[XB_TMO], 1u); break; } } } } while (0)
; DI void xcd_barrier(const XcdBarrier& b) {
;     ...
;       XB_SPIN(xb_ld(&bar[XB_XGEN(b.x)]) == gen, bar);
;       __builtin_amdgcn_fence(__ATOMIC_ACQUIRE, "agent");
;       asm volatile("s_waitcnt vmcnt(0)" ::: "memory");
.LBB0_197:
	s_or_b64 exec, exec, s[14:15]
	s_waitcnt vmcnt(3)
	s_waitcnt vmcnt(3)

; DI unsigned xb_ld(unsigned* p) { return __hip_atomic_load(p, __ATOMIC_RELAXED, __HIP_MEMORY_SCOPE_AGENT); }
; DI unsigned xb_add(unsigned* p, unsigned v) { return __hip_atomic_fetch_add(p, v, __ATOMIC_RELAXED, __HIP_MEMORY_SCOPE_AGENT); }
; #define XB_SPIN(cond, bar) do { unsigned _sp = 0; while (cond) { __builtin_amdgcn_s_sleep(1); \
;     if ((++_sp & 255u) == 0u) { if (xb_ld(&(bar)[XB_TMO])) break; if (_sp > XB_SPIN_CAP) { atomicAdd(&(bar)[XB_TMO], 1u); break; } } } } while (0)
; DI void xcd_barrier(const XcdBarrier& b) {
;     ...
;     if (old + 1u == (gen + 1u) * nloc) {
;       __builtin_amdgcn_fence(__ATOMIC_RELEASE, "agent");
;       asm volatile("s_waitcnt vmcnt(0)" ::: "memory");
;       const unsigned og = xb_add(&bar[XB_TOP], 1u);
;       const unsigned tg = og / nx;
;       if (og + 1u == (tg + 1u) * nx) xb_add(&bar[XB_TOPGEN], 1u);
;       else XB_SPIN(xb_ld(&bar[XB_TOPGEN]) == tg, bar);
.LBB0_201:
	s_or_b64 exec, exec, s[14:15]
	v_cvt_f32_u32_e32 v3, v0
	s_waitcnt vmcnt(0)
	v_readfirstlane_b32 s0, v2
	s_add_u32 s14, s86, 0xe7c4500
	s_addc_u32 s15, s87, 0
	v_rcp_iflag_f32_e32 v3, v3
	v_add_u32_e32 v1, s0, v1
	v_add_u32_e32 v4, 1, v1
	s_mov_b64 s[16:17], -1
	v_mul_f32_e32 v2, 0x4f7ffffe, v3
	v_cvt_u32_f32_e32 v2, v2
	v_sub_u32_e32 v3, 0, v0
	v_mul_lo_u32 v3, v3, v2
	v_mul_hi_u32 v3, v2, v3
	v_add_u32_e32 v2, v2, v3
	v_mul_hi_u32 v2, v1, v2
	v_mul_lo_u32 v3, v2, v0
	v_sub_u32_e32 v1, v1, v3
	v_add_u32_e32 v5, 1, v2
	v_cmp_ge_u32_e32 vcc, v1, v0
	v_sub_u32_e32 v3, v1, v0
	s_nop 0
	v_cndmask_b32_e32 v2, v2, v5, vcc
	v_cndmask_b32_e32 v1, v1, v3, vcc
	v_add_u32_e32 v3, 1, v2
	v_cmp_ge_u32_e32 vcc, v1, v0
	s_nop 1
	v_cndmask_b32_e32 v2, v2, v3, vcc
	v_mul_lo_u32 v1, v0, v2
	v_add_u32_e32 v0, v1, v0
	v_cmp_ne_u32_e32 vcc, v4, v0
	v_mov_b32_e32 v232, v0
	v_mov_b64_e32 v[0:1], s[14:15]
	s_and_saveexec_b64 s[12:13], vcc
	s_cbranch_execz .LBB0_213
	v_mov_b32_e32 v0, 0
	v_mov_b32_e32 v233, 0xe7c4000
	global_load_dword v1, v233, s[86:87] offset:1024 sc1
	s_mov_b64 s[30:31], 0
	s_waitcnt vmcnt(0)
	v_cmp_lt_u32_e32 vcc, v1, v232
	v_mov_b32_e32 v231, v1
	s_and_saveexec_b64 s[20:21], vcc
	s_cbranch_execz .LBB0_212
	s_add_u32 s16, s86, 0xe7c1200
	s_addc_u32 s17, s87, 0
	s_mov_b32 s0, 1
	s_branch .LBB0_205

; DI unsigned xb_ld(unsigned* p) { return __hip_atomic_load(p, __ATOMIC_RELAXED, __HIP_MEMORY_SCOPE_AGENT); }
; #define XB_SPIN(cond, bar) do { unsigned _sp = 0; while (cond) { __builtin_amdgcn_s_sleep(1); \
;     if ((++_sp & 255u) == 0u) { if (xb_ld(&(bar)[XB_TMO])) break; if (_sp > XB_SPIN_CAP) { atomicAdd(&(bar)[XB_TMO], 1u); break; } } } } while (0)
; DI void xcd_barrier(const XcdBarrier& b) {
;     ...
;       else XB_SPIN(xb_ld(&bar[XB_TOPGEN]) == tg, bar);
.LBB0_209:
	global_load_dword v231, v233, s[86:87] offset:1024 sc1
	s_add_i32 s0, s0, 1
	s_mov_b64 s[36:37], -1
	s_waitcnt vmcnt(3)
	v_cmp_ge_u32_e32 vcc, v231, v232
	s_orn2_b64 s[44:45], vcc, exec
	s_branch .LBB0_204

; DI unsigned xb_add(unsigned* p, unsigned v) { return __hip_atomic_fetch_add(p, v, __ATOMIC_RELAXED, __HIP_MEMORY_SCOPE_AGENT); }
; DI void xcd_barrier(const XcdBarrier& b) {
;     ...
;       __builtin_amdgcn_fence(__ATOMIC_ACQUIRE, "agent");
;       xb_add(&bar[XB_XGEN(b.x)], 1u);
;       asm volatile("s_waitcnt vmcnt(0)" ::: "memory");
.LBB0_215:
	s_or_b64 exec, exec, s[12:13]
	s_mov_b64 s[12:13], exec
	v_mbcnt_lo_u32_b32 v0, s12, 0
	v_mbcnt_hi_u32_b32 v0, s13, v0
	v_cmp_eq_u32_e32 vcc, 0, v0
	s_waitcnt vmcnt(3)
	s_and_saveexec_b64 s[14:15], vcc
	s_cbranch_execz .LBB0_217
	s_bcnt1_i32_b64 s0, s[12:13]
	v_mov_b32_e32 v0, 0x2000
	v_mov_b32_e32 v1, s0
	global_atomic_add v0, v1, s[10:11] offset:1024
.LBB0_217:
	s_or_b64 exec, exec, s[14:15]
	s_waitcnt vmcnt(3)

; DI unsigned xb_ld(unsigned* p) { return __hip_atomic_load(p, __ATOMIC_RELAXED, __HIP_MEMORY_SCOPE_AGENT); }
; DI unsigned xb_add(unsigned* p, unsigned v) { return __hip_atomic_fetch_add(p, v, __ATOMIC_RELAXED, __HIP_MEMORY_SCOPE_AGENT); }
; #define XB_SPIN(cond, bar) do { unsigned _sp = 0; while (cond) { __builtin_amdgcn_s_sleep(1); \
;     if ((++_sp & 255u) == 0u) { if (xb_ld(&(bar)[XB_TMO])) break; if (_sp > XB_SPIN_CAP) { atomicAdd(&(bar)[XB_TMO], 1u); break; } } } } while (0)
; DI void xcd_barrier(const XcdBarrier& b) {
;     ...
;     const unsigned old = xb_add(&bar[XB_XSUB(b.x)], 1u);
;     const unsigned gen = old / nloc;
;     if (old + 1u == (gen + 1u) * nloc) {
;       __builtin_amdgcn_fence(__ATOMIC_RELEASE, "agent");
;       asm volatile("s_waitcnt vmcnt(0)" ::: "memory");
;       const unsigned og = xb_add(&bar[XB_TOP], 1u);
;       const unsigned tg = og / nx;
;       if (og + 1u == (tg + 1u) * nx) xb_add(&bar[XB_TOPGEN], 1u);
;       else XB_SPIN(xb_ld(&bar[XB_TOPGEN]) == tg, bar);
;       __builtin_amdgcn_fence(__ATOMIC_ACQUIRE, "agent");
;       xb_add(&bar[XB_XGEN(b.x)], 1u);
;       asm volatile("s_waitcnt vmcnt(0)" ::: "memory");
;     } else {
;       XB_SPIN(xb_ld(&bar[XB_XGEN(b.x)]) == gen, bar);
.LBB0_249:
	s_or_b64 exec, exec, s[12:13]
	v_cvt_f32_u32_e32 v4, v2
	s_waitcnt vmcnt(0)
	v_readfirstlane_b32 s0, v3
	buffer_inv sc1
	v_sub_u32_e32 v3, 0, v2
	v_rcp_iflag_f32_e32 v4, v4
	v_add_u32_e32 v5, s0, v1
	v_mul_f32_e32 v4, 0x4f7ffffe, v4
	v_cvt_u32_f32_e32 v4, v4
	v_mul_lo_u32 v1, v3, v4
	v_mul_hi_u32 v1, v4, v1
	v_add_u32_e32 v1, v4, v1
	v_mul_hi_u32 v1, v5, v1
	v_mul_lo_u32 v3, v1, v2
	v_sub_u32_e32 v3, v5, v3
	v_add_u32_e32 v4, 1, v1
	v_cmp_ge_u32_e32 vcc, v3, v2
	s_nop 1
	v_cndmask_b32_e32 v1, v1, v4, vcc
	v_sub_u32_e32 v4, v3, v2
	v_cndmask_b32_e32 v3, v3, v4, vcc
	v_add_u32_e32 v4, 1, v1
	v_cmp_ge_u32_e32 vcc, v3, v2
	v_add_u32_e32 v3, 1, v5
	s_nop 0
	v_cndmask_b32_e32 v1, v1, v4, vcc
	v_mul_lo_u32 v4, v2, v1
	v_add_u32_e32 v2, v4, v2
	v_cmp_ne_u32_e32 vcc, v3, v2
	s_and_saveexec_b64 s[0:1], vcc
	s_xor_b64 s[10:11], exec, s[0:1]
	s_cbranch_execz .LBB0_263
	s_waitcnt lgkmcnt(0)
	v_mov_b32_e32 v0, 0x2000
	global_load_dword v0, v0, s[8:9] offset:1024 sc1
	s_add_u32 s16, s8, 0x2400
	s_addc_u32 s17, s9, 0
	s_waitcnt vmcnt(0)
	v_cmp_eq_u32_e32 vcc, v0, v1
	v_mov_b32_e32 v231, v1
	s_and_saveexec_b64 s[12:13], vcc
	s_cbranch_execz .LBB0_262
	s_add_u32 s14, s86, 0xe7c1200
	s_addc_u32 s15, s87, 0
	s_mov_b32 s0, 1
	s_mov_b64 s[20:21], 0
	v_mov_b32_e32 v0, 0
	s_branch .LBB0_253

; DI unsigned xb_ld(unsigned* p) { return __hip_atomic_load(p, __ATOMIC_RELAXED, __HIP_MEMORY_SCOPE_AGENT); }
; #define XB_SPIN(cond, bar) do { unsigned _sp = 0; while (cond) { __builtin_amdgcn_s_sleep(1); \
;     if ((++_sp & 255u) == 0u) { if (xb_ld(&(bar)[XB_TMO])) break; if (_sp > XB_SPIN_CAP) { atomicAdd(&(bar)[XB_TMO], 1u); break; } } } } while (0)
; DI void xcd_barrier(const XcdBarrier& b) {
;     ...
;       XB_SPIN(xb_ld(&bar[XB_XGEN(b.x)]) == gen, bar);
.LBB0_257:
	global_load_dword v231, v0, s[16:17] sc1
	s_add_i32 s0, s0, 1
	s_mov_b64 s[42:43], -1
	s_waitcnt vmcnt(3)
	v_cmp_ne_u32_e32 vcc, v231, v1
	s_orn2_b64 s[36:37], vcc, exec
	s_branch .LBB0_252

; DI unsigned xb_ld(unsigned* p) { return __hip_atomic_load(p, __ATOMIC_RELAXED, __HIP_MEMORY_SCOPE_AGENT); }
; #define XB_SPIN(cond, bar) do { unsigned _sp = 0; while (cond) { __builtin_amdgcn_s_sleep(1); \
;     if ((++_sp & 255u) == 0u) { if (xb_ld(&(bar)[XB_TMO])) break; if (_sp > XB_SPIN_CAP) { atomicAdd(&(bar)[XB_TMO], 1u); break; } } } } while (0)
; DI void xcd_barrier(const XcdBarrier& b) {
;     ...
;       XB_SPIN(xb_ld(&bar[XB_XGEN(b.x)]) == gen, bar);
;       __builtin_amdgcn_fence(__ATOMIC_ACQUIRE, "agent");
;       asm volatile("s_waitcnt vmcnt(0)" ::: "memory");
.LBB0_262:
	s_or_b64 exec, exec, s[12:13]
	s_waitcnt vmcnt(3)
	s_waitcnt vmcnt(3)

; DI unsigned xb_ld(unsigned* p) { return __hip_atomic_load(p, __ATOMIC_RELAXED, __HIP_MEMORY_SCOPE_AGENT); }
; DI unsigned xb_add(unsigned* p, unsigned v) { return __hip_atomic_fetch_add(p, v, __ATOMIC_RELAXED, __HIP_MEMORY_SCOPE_AGENT); }
; #define XB_SPIN(cond, bar) do { unsigned _sp = 0; while (cond) { __builtin_amdgcn_s_sleep(1); \
;     if ((++_sp & 255u) == 0u) { if (xb_ld(&(bar)[XB_TMO])) break; if (_sp > XB_SPIN_CAP) { atomicAdd(&(bar)[XB_TMO], 1u); break; } } } } while (0)
; DI void xcd_barrier(const XcdBarrier& b) {
;     ...
;     if (old + 1u == (gen + 1u) * nloc) {
;       __builtin_amdgcn_fence(__ATOMIC_RELEASE, "agent");
;       asm volatile("s_waitcnt vmcnt(0)" ::: "memory");
;       const unsigned og = xb_add(&bar[XB_TOP], 1u);
;       const unsigned tg = og / nx;
;       if (og + 1u == (tg + 1u) * nx) xb_add(&bar[XB_TOPGEN], 1u);
;       else XB_SPIN(xb_ld(&bar[XB_TOPGEN]) == tg, bar);
.LBB0_266:
	s_or_b64 exec, exec, s[12:13]
	v_cvt_f32_u32_e32 v3, v0
	s_waitcnt vmcnt(0)
	v_readfirstlane_b32 s0, v2
	s_add_u32 s12, s86, 0xe7c4500
	s_addc_u32 s13, s87, 0
	v_rcp_iflag_f32_e32 v3, v3
	v_add_u32_e32 v1, s0, v1
	v_add_u32_e32 v4, 1, v1
	s_mov_b64 s[14:15], -1
	v_mul_f32_e32 v2, 0x4f7ffffe, v3
	v_cvt_u32_f32_e32 v2, v2
	v_sub_u32_e32 v3, 0, v0
	v_mul_lo_u32 v3, v3, v2
	v_mul_hi_u32 v3, v2, v3
	v_add_u32_e32 v2, v2, v3
	v_mul_hi_u32 v2, v1, v2
	v_mul_lo_u32 v3, v2, v0
	v_sub_u32_e32 v1, v1, v3
	v_add_u32_e32 v5, 1, v2
	v_cmp_ge_u32_e32 vcc, v1, v0
	v_sub_u32_e32 v3, v1, v0
	s_nop 0
	v_cndmask_b32_e32 v2, v2, v5, vcc
	v_cndmask_b32_e32 v1, v1, v3, vcc
	v_add_u32_e32 v3, 1, v2
	v_cmp_ge_u32_e32 vcc, v1, v0
	s_nop 1
	v_cndmask_b32_e32 v2, v2, v3, vcc
	v_mul_lo_u32 v1, v0, v2
	v_add_u32_e32 v0, v1, v0
	v_cmp_ne_u32_e32 vcc, v4, v0
	v_mov_b32_e32 v232, v0
	v_mov_b64_e32 v[0:1], s[12:13]
	s_and_saveexec_b64 s[10:11], vcc
	s_cbranch_execz .LBB0_278
	v_mov_b32_e32 v0, 0
	v_mov_b32_e32 v233, 0xe7c4000
	global_load_dword v1, v233, s[86:87] offset:1024 sc1
	s_mov_b64 s[20:21], 0
	s_waitcnt vmcnt(0)
	v_cmp_lt_u32_e32 vcc, v1, v232
	v_mov_b32_e32 v231, v1
	s_and_saveexec_b64 s[16:17], vcc
	s_cbranch_execz .LBB0_277
	s_add_u32 s14, s86, 0xe7c1200
	s_addc_u32 s15, s87, 0
	s_mov_b32 s0, 1
	s_branch .LBB0_270

; DI unsigned xb_add(unsigned* p, unsigned v) { return __hip_atomic_fetch_add(p, v, __ATOMIC_RELAXED, __HIP_MEMORY_SCOPE_AGENT); }
; DI void xcd_barrier(const XcdBarrier& b) {
;     ...
;       __builtin_amdgcn_fence(__ATOMIC_ACQUIRE, "agent");
;       xb_add(&bar[XB_XGEN(b.x)], 1u);
;       asm volatile("s_waitcnt vmcnt(0)" ::: "memory");
.LBB0_280:
	s_or_b64 exec, exec, s[10:11]
	s_mov_b64 s[10:11], exec
	v_mbcnt_lo_u32_b32 v0, s10, 0
	v_mbcnt_hi_u32_b32 v0, s11, v0
	v_cmp_eq_u32_e32 vcc, 0, v0
	s_waitcnt vmcnt(3)
	s_and_saveexec_b64 s[12:13], vcc
	s_cbranch_execz .LBB0_282
	s_bcnt1_i32_b64 s0, s[10:11]
	v_mov_b32_e32 v0, 0x2000
	v_mov_b32_e32 v1, s0
	global_atomic_add v0, v1, s[8:9] offset:1024
.LBB0_282:
	s_or_b64 exec, exec, s[12:13]
	s_waitcnt vmcnt(3)

; DI unsigned xb_ld(unsigned* p) { return __hip_atomic_load(p, __ATOMIC_RELAXED, __HIP_MEMORY_SCOPE_AGENT); }
; DI unsigned xb_add(unsigned* p, unsigned v) { return __hip_atomic_fetch_add(p, v, __ATOMIC_RELAXED, __HIP_MEMORY_SCOPE_AGENT); }
; #define XB_SPIN(cond, bar) do { unsigned _sp = 0; while (cond) { __builtin_amdgcn_s_sleep(1); \
;     if ((++_sp & 255u) == 0u) { if (xb_ld(&(bar)[XB_TMO])) break; if (_sp > XB_SPIN_CAP) { atomicAdd(&(bar)[XB_TMO], 1u); break; } } } } while (0)
; DI void xcd_barrier(const XcdBarrier& b) {
;     ...
;     const unsigned old = xb_add(&bar[XB_XSUB(b.x)], 1u);
;     const unsigned gen = old / nloc;
;     if (old + 1u == (gen + 1u) * nloc) {
;       __builtin_amdgcn_fence(__ATOMIC_RELEASE, "agent");
;       asm volatile("s_waitcnt vmcnt(0)" ::: "memory");
;       const unsigned og = xb_add(&bar[XB_TOP], 1u);
;       const unsigned tg = og / nx;
;       if (og + 1u == (tg + 1u) * nx) xb_add(&bar[XB_TOPGEN], 1u);
;       else XB_SPIN(xb_ld(&bar[XB_TOPGEN]) == tg, bar);
;       __builtin_amdgcn_fence(__ATOMIC_ACQUIRE, "agent");
;       xb_add(&bar[XB_XGEN(b.x)], 1u);
;       asm volatile("s_waitcnt vmcnt(0)" ::: "memory");
;     } else {
;       XB_SPIN(xb_ld(&bar[XB_XGEN(b.x)]) == gen, bar);
.LBB0_490:
	s_or_b64 exec, exec, s[12:13]
	v_cvt_f32_u32_e32 v4, v2
	s_waitcnt vmcnt(0)
	v_readfirstlane_b32 s0, v3
	buffer_inv sc1
	v_sub_u32_e32 v3, 0, v2
	v_rcp_iflag_f32_e32 v4, v4
	v_add_u32_e32 v5, s0, v1
	v_mul_f32_e32 v4, 0x4f7ffffe, v4
	v_cvt_u32_f32_e32 v4, v4
	v_mul_lo_u32 v1, v3, v4
	v_mul_hi_u32 v1, v4, v1
	v_add_u32_e32 v1, v4, v1
	v_mul_hi_u32 v1, v5, v1
	v_mul_lo_u32 v3, v1, v2
	v_sub_u32_e32 v3, v5, v3
	v_add_u32_e32 v4, 1, v1
	v_cmp_ge_u32_e32 vcc, v3, v2
	s_nop 1
	v_cndmask_b32_e32 v1, v1, v4, vcc
	v_sub_u32_e32 v4, v3, v2
	v_cndmask_b32_e32 v3, v3, v4, vcc
	v_add_u32_e32 v4, 1, v1
	v_cmp_ge_u32_e32 vcc, v3, v2
	v_add_u32_e32 v3, 1, v5
	s_nop 0
	v_cndmask_b32_e32 v1, v1, v4, vcc
	v_mul_lo_u32 v4, v2, v1
	v_add_u32_e32 v2, v4, v2
	v_cmp_ne_u32_e32 vcc, v3, v2
	s_and_saveexec_b64 s[0:1], vcc
	s_xor_b64 s[10:11], exec, s[0:1]
	s_cbranch_execz .LBB0_504
	s_waitcnt lgkmcnt(0)
	v_mov_b32_e32 v0, 0x2000
	global_load_dword v0, v0, s[8:9] offset:1024 sc1
	s_add_u32 s16, s8, 0x2400
	s_addc_u32 s17, s9, 0
	s_waitcnt vmcnt(0)
	v_cmp_eq_u32_e32 vcc, v0, v1
	v_mov_b32_e32 v231, v1
	s_and_saveexec_b64 s[12:13], vcc
	s_cbranch_execz .LBB0_503
	s_add_u32 s14, s86, 0xe7c1200
	s_addc_u32 s15, s87, 0
	s_mov_b32 s0, 1
	s_mov_b64 s[30:31], 0
	v_mov_b32_e32 v0, 0
	s_branch .LBB0_494

; DI unsigned xb_ld(unsigned* p) { return __hip_atomic_load(p, __ATOMIC_RELAXED, __HIP_MEMORY_SCOPE_AGENT); }
; DI unsigned xb_add(unsigned* p, unsigned v) { return __hip_atomic_fetch_add(p, v, __ATOMIC_RELAXED, __HIP_MEMORY_SCOPE_AGENT); }
; #define XB_SPIN(cond, bar) do { unsigned _sp = 0; while (cond) { __builtin_amdgcn_s_sleep(1); \
;     if ((++_sp & 255u) == 0u) { if (xb_ld(&(bar)[XB_TMO])) break; if (_sp > XB_SPIN_CAP) { atomicAdd(&(bar)[XB_TMO], 1u); break; } } } } while (0)
; DI void xcd_barrier(const XcdBarrier& b) {
;     ...
;     if (old + 1u == (gen + 1u) * nloc) {
;       __builtin_amdgcn_fence(__ATOMIC_RELEASE, "agent");
;       asm volatile("s_waitcnt vmcnt(0)" ::: "memory");
;       const unsigned og = xb_add(&bar[XB_TOP], 1u);
;       const unsigned tg = og / nx;
;       if (og + 1u == (tg + 1u) * nx) xb_add(&bar[XB_TOPGEN], 1u);
;       else XB_SPIN(xb_ld(&bar[XB_TOPGEN]) == tg, bar);
.LBB0_507:
	s_or_b64 exec, exec, s[12:13]
	v_cvt_f32_u32_e32 v3, v0
	s_waitcnt vmcnt(0)
	v_readfirstlane_b32 s0, v2
	s_add_u32 s12, s86, 0xe7c4500
	s_addc_u32 s13, s87, 0
	v_rcp_iflag_f32_e32 v3, v3
	v_add_u32_e32 v1, s0, v1
	v_add_u32_e32 v4, 1, v1
	s_mov_b64 s[14:15], -1
	v_mul_f32_e32 v2, 0x4f7ffffe, v3
	v_cvt_u32_f32_e32 v2, v2
	v_sub_u32_e32 v3, 0, v0
	v_mul_lo_u32 v3, v3, v2
	v_mul_hi_u32 v3, v2, v3
	v_add_u32_e32 v2, v2, v3
	v_mul_hi_u32 v2, v1, v2
	v_mul_lo_u32 v3, v2, v0
	v_sub_u32_e32 v1, v1, v3
	v_add_u32_e32 v5, 1, v2
	v_cmp_ge_u32_e32 vcc, v1, v0
	v_sub_u32_e32 v3, v1, v0
	s_nop 0
	v_cndmask_b32_e32 v2, v2, v5, vcc
	v_cndmask_b32_e32 v1, v1, v3, vcc
	v_add_u32_e32 v3, 1, v2
	v_cmp_ge_u32_e32 vcc, v1, v0
	s_nop 1
	v_cndmask_b32_e32 v2, v2, v3, vcc
	v_mul_lo_u32 v1, v0, v2
	v_add_u32_e32 v0, v1, v0
	v_cmp_ne_u32_e32 vcc, v4, v0
	v_mov_b32_e32 v232, v0
	v_mov_b64_e32 v[0:1], s[12:13]
	s_and_saveexec_b64 s[10:11], vcc
	s_cbranch_execz .LBB0_519
	v_mov_b32_e32 v0, 0
	v_mov_b32_e32 v233, 0xe7c4000
	global_load_dword v1, v233, s[86:87] offset:1024 sc1
	s_mov_b64 s[30:31], 0
	s_waitcnt vmcnt(0)
	v_cmp_lt_u32_e32 vcc, v1, v232
	v_mov_b32_e32 v231, v1
	s_and_saveexec_b64 s[16:17], vcc
	s_cbranch_execz .LBB0_518
	s_add_u32 s14, s86, 0xe7c1200
	s_addc_u32 s15, s87, 0
	s_mov_b32 s0, 1
	s_branch .LBB0_511

; DI unsigned xb_ld(unsigned* p) { return __hip_atomic_load(p, __ATOMIC_RELAXED, __HIP_MEMORY_SCOPE_AGENT); }
; DI unsigned xb_add(unsigned* p, unsigned v) { return __hip_atomic_fetch_add(p, v, __ATOMIC_RELAXED, __HIP_MEMORY_SCOPE_AGENT); }
; #define XB_SPIN(cond, bar) do { unsigned _sp = 0; while (cond) { __builtin_amdgcn_s_sleep(1); \
;     if ((++_sp & 255u) == 0u) { if (xb_ld(&(bar)[XB_TMO])) break; if (_sp > XB_SPIN_CAP) { atomicAdd(&(bar)[XB_TMO], 1u); break; } } } } while (0)
; DI void xcd_barrier(const XcdBarrier& b) {
;     ...
;     const unsigned old = xb_add(&bar[XB_XSUB(b.x)], 1u);
;     const unsigned gen = old / nloc;
;     if (old + 1u == (gen + 1u) * nloc) {
;       __builtin_amdgcn_fence(__ATOMIC_RELEASE, "agent");
;       asm volatile("s_waitcnt vmcnt(0)" ::: "memory");
;       const unsigned og = xb_add(&bar[XB_TOP], 1u);
;       const unsigned tg = og / nx;
;       if (og + 1u == (tg + 1u) * nx) xb_add(&bar[XB_TOPGEN], 1u);
;       else XB_SPIN(xb_ld(&bar[XB_TOPGEN]) == tg, bar);
;       __builtin_amdgcn_fence(__ATOMIC_ACQUIRE, "agent");
;       xb_add(&bar[XB_XGEN(b.x)], 1u);
;       asm volatile("s_waitcnt vmcnt(0)" ::: "memory");
;     } else {
;       XB_SPIN(xb_ld(&bar[XB_XGEN(b.x)]) == gen, bar);
.LBB0_829:
	s_or_b64 exec, exec, s[12:13]
	v_cvt_f32_u32_e32 v4, v2
	s_waitcnt vmcnt(0)
	v_readfirstlane_b32 s0, v3
	buffer_inv sc1
	v_sub_u32_e32 v3, 0, v2
	v_rcp_iflag_f32_e32 v4, v4
	v_add_u32_e32 v5, s0, v1
	v_mul_f32_e32 v4, 0x4f7ffffe, v4
	v_cvt_u32_f32_e32 v4, v4
	v_mul_lo_u32 v1, v3, v4
	v_mul_hi_u32 v1, v4, v1
	v_add_u32_e32 v1, v4, v1
	v_mul_hi_u32 v1, v5, v1
	v_mul_lo_u32 v3, v1, v2
	v_sub_u32_e32 v3, v5, v3
	v_add_u32_e32 v4, 1, v1
	v_cmp_ge_u32_e32 vcc, v3, v2
	s_nop 1
	v_cndmask_b32_e32 v1, v1, v4, vcc
	v_sub_u32_e32 v4, v3, v2
	v_cndmask_b32_e32 v3, v3, v4, vcc
	v_add_u32_e32 v4, 1, v1
	v_cmp_ge_u32_e32 vcc, v3, v2
	v_add_u32_e32 v3, 1, v5
	s_nop 0
	v_cndmask_b32_e32 v1, v1, v4, vcc
	v_mul_lo_u32 v4, v2, v1
	v_add_u32_e32 v2, v4, v2
	v_cmp_ne_u32_e32 vcc, v3, v2
	s_and_saveexec_b64 s[0:1], vcc
	s_xor_b64 s[10:11], exec, s[0:1]
	s_cbranch_execz .LBB0_843
	s_waitcnt lgkmcnt(0)
	v_mov_b32_e32 v0, 0x2000
	global_load_dword v0, v0, s[8:9] offset:1024 sc1
	s_add_u32 s16, s8, 0x2400
	s_addc_u32 s17, s9, 0
	s_waitcnt vmcnt(0)
	v_cmp_eq_u32_e32 vcc, v0, v1
	v_mov_b32_e32 v231, v1
	s_and_saveexec_b64 s[12:13], vcc
	s_cbranch_execz .LBB0_842
	s_add_u32 s14, s86, 0xe7c1200
	s_addc_u32 s15, s87, 0
	s_mov_b32 s0, 1
	s_mov_b64 s[26:27], 0
	v_mov_b32_e32 v0, 0
	s_branch .LBB0_833

; DI unsigned xb_ld(unsigned* p) { return __hip_atomic_load(p, __ATOMIC_RELAXED, __HIP_MEMORY_SCOPE_AGENT); }
; #define XB_SPIN(cond, bar) do { unsigned _sp = 0; while (cond) { __builtin_amdgcn_s_sleep(1); \
;     if ((++_sp & 255u) == 0u) { if (xb_ld(&(bar)[XB_TMO])) break; if (_sp > XB_SPIN_CAP) { atomicAdd(&(bar)[XB_TMO], 1u); break; } } } } while (0)
; DI void xcd_barrier(const XcdBarrier& b) {
;     ...
;       XB_SPIN(xb_ld(&bar[XB_XGEN(b.x)]) == gen, bar);
.LBB0_837:
	global_load_dword v231, v0, s[16:17] sc1
	s_add_i32 s0, s0, 1
	s_mov_b64 s[34:35], -1
	s_waitcnt vmcnt(3)
	v_cmp_ne_u32_e32 vcc, v231, v1
	s_orn2_b64 s[30:31], vcc, exec
	s_branch .LBB0_832

; DI unsigned xb_ld(unsigned* p) { return __hip_atomic_load(p, __ATOMIC_RELAXED, __HIP_MEMORY_SCOPE_AGENT); }
; DI unsigned xb_add(unsigned* p, unsigned v) { return __hip_atomic_fetch_add(p, v, __ATOMIC_RELAXED, __HIP_MEMORY_SCOPE_AGENT); }
; #define XB_SPIN(cond, bar) do { unsigned _sp = 0; while (cond) { __builtin_amdgcn_s_sleep(1); \
;     if ((++_sp & 255u) == 0u) { if (xb_ld(&(bar)[XB_TMO])) break; if (_sp > XB_SPIN_CAP) { atomicAdd(&(bar)[XB_TMO], 1u); break; } } } } while (0)
; DI void xcd_barrier(const XcdBarrier& b) {
;     ...
;     if (old + 1u == (gen + 1u) * nloc) {
;       __builtin_amdgcn_fence(__ATOMIC_RELEASE, "agent");
;       asm volatile("s_waitcnt vmcnt(0)" ::: "memory");
;       const unsigned og = xb_add(&bar[XB_TOP], 1u);
;       const unsigned tg = og / nx;
;       if (og + 1u == (tg + 1u) * nx) xb_add(&bar[XB_TOPGEN], 1u);
;       else XB_SPIN(xb_ld(&bar[XB_TOPGEN]) == tg, bar);
.LBB0_846:
	s_or_b64 exec, exec, s[12:13]
	v_cvt_f32_u32_e32 v3, v0
	s_waitcnt vmcnt(0)
	v_readfirstlane_b32 s0, v2
	s_add_u32 s12, s86, 0xe7c4500
	s_addc_u32 s13, s87, 0
	v_rcp_iflag_f32_e32 v3, v3
	v_add_u32_e32 v1, s0, v1
	v_add_u32_e32 v4, 1, v1
	s_mov_b64 s[14:15], -1
	v_mul_f32_e32 v2, 0x4f7ffffe, v3
	v_cvt_u32_f32_e32 v2, v2
	v_sub_u32_e32 v3, 0, v0
	v_mul_lo_u32 v3, v3, v2
	v_mul_hi_u32 v3, v2, v3
	v_add_u32_e32 v2, v2, v3
	v_mul_hi_u32 v2, v1, v2
	v_mul_lo_u32 v3, v2, v0
	v_sub_u32_e32 v1, v1, v3
	v_add_u32_e32 v5, 1, v2
	v_cmp_ge_u32_e32 vcc, v1, v0
	v_sub_u32_e32 v3, v1, v0
	s_nop 0
	v_cndmask_b32_e32 v2, v2, v5, vcc
	v_cndmask_b32_e32 v1, v1, v3, vcc
	v_add_u32_e32 v3, 1, v2
	v_cmp_ge_u32_e32 vcc, v1, v0
	s_nop 1
	v_cndmask_b32_e32 v2, v2, v3, vcc
	v_mul_lo_u32 v1, v0, v2
	v_add_u32_e32 v0, v1, v0
	v_cmp_ne_u32_e32 vcc, v4, v0
	v_mov_b32_e32 v232, v0
	v_mov_b64_e32 v[0:1], s[12:13]
	s_and_saveexec_b64 s[10:11], vcc
	s_cbranch_execz .LBB0_858
	v_mov_b32_e32 v0, 0
	v_mov_b32_e32 v233, 0xe7c4000
	global_load_dword v1, v233, s[86:87] offset:1024 sc1
	s_mov_b64 s[26:27], 0
	s_waitcnt vmcnt(0)
	v_cmp_lt_u32_e32 vcc, v1, v232
	v_mov_b32_e32 v231, v1
	s_and_saveexec_b64 s[16:17], vcc
	s_cbranch_execz .LBB0_857
	s_add_u32 s14, s86, 0xe7c1200
	s_addc_u32 s15, s87, 0
	s_mov_b32 s0, 1
	s_branch .LBB0_850

; DI unsigned xb_ld(unsigned* p) { return __hip_atomic_load(p, __ATOMIC_RELAXED, __HIP_MEMORY_SCOPE_AGENT); }
; #define XB_SPIN(cond, bar) do { unsigned _sp = 0; while (cond) { __builtin_amdgcn_s_sleep(1); \
;     if ((++_sp & 255u) == 0u) { if (xb_ld(&(bar)[XB_TMO])) break; if (_sp > XB_SPIN_CAP) { atomicAdd(&(bar)[XB_TMO], 1u); break; } } } } while (0)
; DI void xcd_barrier(const XcdBarrier& b) {
;     ...
;       else XB_SPIN(xb_ld(&bar[XB_TOPGEN]) == tg, bar);
.LBB0_854:
	global_load_dword v231, v233, s[86:87] offset:1024 sc1
	s_add_i32 s0, s0, 1
	s_mov_b64 s[30:31], -1
	s_waitcnt vmcnt(3)
	v_cmp_ge_u32_e32 vcc, v231, v232
	s_orn2_b64 s[36:37], vcc, exec
	s_branch .LBB0_849

; DI unsigned xb_ld(unsigned* p) { return __hip_atomic_load(p, __ATOMIC_RELAXED, __HIP_MEMORY_SCOPE_AGENT); }
; DI unsigned xb_add(unsigned* p, unsigned v) { return __hip_atomic_fetch_add(p, v, __ATOMIC_RELAXED, __HIP_MEMORY_SCOPE_AGENT); }
; #define XB_SPIN(cond, bar) do { unsigned _sp = 0; while (cond) { __builtin_amdgcn_s_sleep(1); \
;     if ((++_sp & 255u) == 0u) { if (xb_ld(&(bar)[XB_TMO])) break; if (_sp > XB_SPIN_CAP) { atomicAdd(&(bar)[XB_TMO], 1u); break; } } } } while (0)
; DI void xcd_barrier(const XcdBarrier& b) {
;     ...
;     const unsigned old = xb_add(&bar[XB_XSUB(b.x)], 1u);
;     const unsigned gen = old / nloc;
;     if (old + 1u == (gen + 1u) * nloc) {
;       __builtin_amdgcn_fence(__ATOMIC_RELEASE, "agent");
;       asm volatile("s_waitcnt vmcnt(0)" ::: "memory");
;       const unsigned og = xb_add(&bar[XB_TOP], 1u);
;       const unsigned tg = og / nx;
;       if (og + 1u == (tg + 1u) * nx) xb_add(&bar[XB_TOPGEN], 1u);
;       else XB_SPIN(xb_ld(&bar[XB_TOPGEN]) == tg, bar);
;       __builtin_amdgcn_fence(__ATOMIC_ACQUIRE, "agent");
;       xb_add(&bar[XB_XGEN(b.x)], 1u);
;       asm volatile("s_waitcnt vmcnt(0)" ::: "memory");
;     } else {
;       XB_SPIN(xb_ld(&bar[XB_XGEN(b.x)]) == gen, bar);
.LBB0_941:
	s_or_b64 exec, exec, s[12:13]
	v_cvt_f32_u32_e32 v4, v2
	s_waitcnt vmcnt(0)
	v_readfirstlane_b32 s0, v3
	buffer_inv sc1
	v_sub_u32_e32 v3, 0, v2
	v_rcp_iflag_f32_e32 v4, v4
	v_add_u32_e32 v5, s0, v1
	v_mul_f32_e32 v4, 0x4f7ffffe, v4
	v_cvt_u32_f32_e32 v4, v4
	v_mul_lo_u32 v1, v3, v4
	v_mul_hi_u32 v1, v4, v1
	v_add_u32_e32 v1, v4, v1
	v_mul_hi_u32 v1, v5, v1
	v_mul_lo_u32 v3, v1, v2
	v_sub_u32_e32 v3, v5, v3
	v_add_u32_e32 v4, 1, v1
	v_cmp_ge_u32_e32 vcc, v3, v2
	s_nop 1
	v_cndmask_b32_e32 v1, v1, v4, vcc
	v_sub_u32_e32 v4, v3, v2
	v_cndmask_b32_e32 v3, v3, v4, vcc
	v_add_u32_e32 v4, 1, v1
	v_cmp_ge_u32_e32 vcc, v3, v2
	v_add_u32_e32 v3, 1, v5
	s_nop 0
	v_cndmask_b32_e32 v1, v1, v4, vcc
	v_mul_lo_u32 v4, v2, v1
	v_add_u32_e32 v2, v4, v2
	v_cmp_ne_u32_e32 vcc, v3, v2
	s_and_saveexec_b64 s[0:1], vcc
	s_xor_b64 s[10:11], exec, s[0:1]
	s_cbranch_execz .LBB0_955
	s_waitcnt lgkmcnt(0)
	v_mov_b32_e32 v0, 0x2000
	global_load_dword v0, v0, s[8:9] offset:1024 sc1
	s_add_u32 s16, s8, 0x2400
	s_addc_u32 s17, s9, 0
	s_waitcnt vmcnt(0)
	v_cmp_eq_u32_e32 vcc, v0, v1
	v_mov_b32_e32 v231, v1
	s_and_saveexec_b64 s[12:13], vcc
	s_cbranch_execz .LBB0_954
	s_add_u32 s14, s86, 0xe7c1200
	s_addc_u32 s15, s87, 0
	s_mov_b32 s0, 1
	s_mov_b64 s[24:25], 0
	v_mov_b32_e32 v0, 0
	s_branch .LBB0_945

; DI unsigned xb_ld(unsigned* p) { return __hip_atomic_load(p, __ATOMIC_RELAXED, __HIP_MEMORY_SCOPE_AGENT); }
; #define XB_SPIN(cond, bar) do { unsigned _sp = 0; while (cond) { __builtin_amdgcn_s_sleep(1); \
;     if ((++_sp & 255u) == 0u) { if (xb_ld(&(bar)[XB_TMO])) break; if (_sp > XB_SPIN_CAP) { atomicAdd(&(bar)[XB_TMO], 1u); break; } } } } while (0)
; DI void xcd_barrier(const XcdBarrier& b) {
;     ...
;       XB_SPIN(xb_ld(&bar[XB_XGEN(b.x)]) == gen, bar);
.LBB0_949:
	global_load_dword v231, v0, s[16:17] sc1
	s_add_i32 s0, s0, 1
	s_mov_b64 s[30:31], -1
	s_waitcnt vmcnt(3)
	v_cmp_ne_u32_e32 vcc, v231, v1
	s_orn2_b64 s[28:29], vcc, exec
	s_branch .LBB0_944

; DI unsigned xb_ld(unsigned* p) { return __hip_atomic_load(p, __ATOMIC_RELAXED, __HIP_MEMORY_SCOPE_AGENT); }
; DI unsigned xb_add(unsigned* p, unsigned v) { return __hip_atomic_fetch_add(p, v, __ATOMIC_RELAXED, __HIP_MEMORY_SCOPE_AGENT); }
; #define XB_SPIN(cond, bar) do { unsigned _sp = 0; while (cond) { __builtin_amdgcn_s_sleep(1); \
;     if ((++_sp & 255u) == 0u) { if (xb_ld(&(bar)[XB_TMO])) break; if (_sp > XB_SPIN_CAP) { atomicAdd(&(bar)[XB_TMO], 1u); break; } } } } while (0)
; DI void xcd_barrier(const XcdBarrier& b) {
;     ...
;     if (old + 1u == (gen + 1u) * nloc) {
;       __builtin_amdgcn_fence(__ATOMIC_RELEASE, "agent");
;       asm volatile("s_waitcnt vmcnt(0)" ::: "memory");
;       const unsigned og = xb_add(&bar[XB_TOP], 1u);
;       const unsigned tg = og / nx;
;       if (og + 1u == (tg + 1u) * nx) xb_add(&bar[XB_TOPGEN], 1u);
;       else XB_SPIN(xb_ld(&bar[XB_TOPGEN]) == tg, bar);
.LBB0_958:
	s_or_b64 exec, exec, s[12:13]
	v_cvt_f32_u32_e32 v3, v0
	s_waitcnt vmcnt(0)
	v_readfirstlane_b32 s0, v2
	s_add_u32 s12, s86, 0xe7c4500
	s_addc_u32 s13, s87, 0
	v_rcp_iflag_f32_e32 v3, v3
	v_add_u32_e32 v1, s0, v1
	v_add_u32_e32 v4, 1, v1
	s_mov_b64 s[14:15], -1
	v_mul_f32_e32 v2, 0x4f7ffffe, v3
	v_cvt_u32_f32_e32 v2, v2
	v_sub_u32_e32 v3, 0, v0
	v_mul_lo_u32 v3, v3, v2
	v_mul_hi_u32 v3, v2, v3
	v_add_u32_e32 v2, v2, v3
	v_mul_hi_u32 v2, v1, v2
	v_mul_lo_u32 v3, v2, v0
	v_sub_u32_e32 v1, v1, v3
	v_add_u32_e32 v5, 1, v2
	v_cmp_ge_u32_e32 vcc, v1, v0
	v_sub_u32_e32 v3, v1, v0
	s_nop 0
	v_cndmask_b32_e32 v2, v2, v5, vcc
	v_cndmask_b32_e32 v1, v1, v3, vcc
	v_add_u32_e32 v3, 1, v2
	v_cmp_ge_u32_e32 vcc, v1, v0
	s_nop 1
	v_cndmask_b32_e32 v2, v2, v3, vcc
	v_mul_lo_u32 v1, v0, v2
	v_add_u32_e32 v0, v1, v0
	v_cmp_ne_u32_e32 vcc, v4, v0
	v_mov_b32_e32 v232, v0
	v_mov_b64_e32 v[0:1], s[12:13]
	s_and_saveexec_b64 s[10:11], vcc
	s_cbranch_execz .LBB0_970
	v_mov_b32_e32 v0, 0
	v_mov_b32_e32 v233, 0xe7c4000
	global_load_dword v1, v233, s[86:87] offset:1024 sc1
	s_mov_b64 s[24:25], 0
	s_waitcnt vmcnt(0)
	v_cmp_lt_u32_e32 vcc, v1, v232
	v_mov_b32_e32 v231, v1
	s_and_saveexec_b64 s[16:17], vcc
	s_cbranch_execz .LBB0_969
	s_add_u32 s14, s86, 0xe7c1200
	s_addc_u32 s15, s87, 0
	s_mov_b32 s0, 1
	s_branch .LBB0_962

; DI unsigned xb_ld(unsigned* p) { return __hip_atomic_load(p, __ATOMIC_RELAXED, __HIP_MEMORY_SCOPE_AGENT); }
; #define XB_SPIN(cond, bar) do { unsigned _sp = 0; while (cond) { __builtin_amdgcn_s_sleep(1); \
;     if ((++_sp & 255u) == 0u) { if (xb_ld(&(bar)[XB_TMO])) break; if (_sp > XB_SPIN_CAP) { atomicAdd(&(bar)[XB_TMO], 1u); break; } } } } while (0)
; DI void xcd_barrier(const XcdBarrier& b) {
;     ...
;       else XB_SPIN(xb_ld(&bar[XB_TOPGEN]) == tg, bar);
.LBB0_966:
	global_load_dword v231, v233, s[86:87] offset:1024 sc1
	s_add_i32 s0, s0, 1
	s_mov_b64 s[28:29], -1
	s_waitcnt vmcnt(3)
	v_cmp_ge_u32_e32 vcc, v231, v232
	s_orn2_b64 s[34:35], vcc, exec
	s_branch .LBB0_961

; DI unsigned xb_ld(unsigned* p) { return __hip_atomic_load(p, __ATOMIC_RELAXED, __HIP_MEMORY_SCOPE_AGENT); }
; DI unsigned xb_add(unsigned* p, unsigned v) { return __hip_atomic_fetch_add(p, v, __ATOMIC_RELAXED, __HIP_MEMORY_SCOPE_AGENT); }
; #define XB_SPIN(cond, bar) do { unsigned _sp = 0; while (cond) { __builtin_amdgcn_s_sleep(1); \
;     if ((++_sp & 255u) == 0u) { if (xb_ld(&(bar)[XB_TMO])) break; if (_sp > XB_SPIN_CAP) { atomicAdd(&(bar)[XB_TMO], 1u); break; } } } } while (0)
; DI void xcd_barrier(const XcdBarrier& b) {
;     ...
;     const unsigned old = xb_add(&bar[XB_XSUB(b.x)], 1u);
;     const unsigned gen = old / nloc;
;     if (old + 1u == (gen + 1u) * nloc) {
;       __builtin_amdgcn_fence(__ATOMIC_RELEASE, "agent");
;       asm volatile("s_waitcnt vmcnt(0)" ::: "memory");
;       const unsigned og = xb_add(&bar[XB_TOP], 1u);
;       const unsigned tg = og / nx;
;       if (og + 1u == (tg + 1u) * nx) xb_add(&bar[XB_TOPGEN], 1u);
;       else XB_SPIN(xb_ld(&bar[XB_TOPGEN]) == tg, bar);
;       __builtin_amdgcn_fence(__ATOMIC_ACQUIRE, "agent");
;       xb_add(&bar[XB_XGEN(b.x)], 1u);
;       asm volatile("s_waitcnt vmcnt(0)" ::: "memory");
;     } else {
;       XB_SPIN(xb_ld(&bar[XB_XGEN(b.x)]) == gen, bar);
.LBB0_1067:
	s_or_b64 exec, exec, s[22:23]
	v_cvt_f32_u32_e32 v4, v2
	s_waitcnt vmcnt(0)
	v_readfirstlane_b32 s0, v3
	buffer_inv sc1
	v_sub_u32_e32 v3, 0, v2
	v_rcp_iflag_f32_e32 v4, v4
	v_add_u32_e32 v5, s0, v1
	v_mul_f32_e32 v4, 0x4f7ffffe, v4
	v_cvt_u32_f32_e32 v4, v4
	v_mul_lo_u32 v1, v3, v4
	v_mul_hi_u32 v1, v4, v1
	v_add_u32_e32 v1, v4, v1
	v_mul_hi_u32 v1, v5, v1
	v_mul_lo_u32 v3, v1, v2
	v_sub_u32_e32 v3, v5, v3
	v_add_u32_e32 v4, 1, v1
	v_cmp_ge_u32_e32 vcc, v3, v2
	s_nop 1
	v_cndmask_b32_e32 v1, v1, v4, vcc
	v_sub_u32_e32 v4, v3, v2
	v_cndmask_b32_e32 v3, v3, v4, vcc
	v_add_u32_e32 v4, 1, v1
	v_cmp_ge_u32_e32 vcc, v3, v2
	v_add_u32_e32 v3, 1, v5
	s_nop 0
	v_cndmask_b32_e32 v1, v1, v4, vcc
	v_mul_lo_u32 v4, v2, v1
	v_add_u32_e32 v2, v4, v2
	v_cmp_ne_u32_e32 vcc, v3, v2
	s_and_saveexec_b64 s[0:1], vcc
	s_xor_b64 s[16:17], exec, s[0:1]
	s_cbranch_execz .LBB0_1081
	s_waitcnt lgkmcnt(0)
	v_mov_b32_e32 v0, 0x2000
	global_load_dword v0, v0, s[14:15] offset:1024 sc1
	s_add_u32 s26, s14, 0x2400
	s_addc_u32 s27, s15, 0
	s_waitcnt vmcnt(0)
	v_cmp_eq_u32_e32 vcc, v0, v1
	v_mov_b32_e32 v231, v1
	s_and_saveexec_b64 s[22:23], vcc
	s_cbranch_execz .LBB0_1080
	s_add_u32 s24, s86, 0xe7c1200
	s_addc_u32 s25, s87, 0
	s_mov_b32 s0, 1
	s_mov_b64 s[28:29], 0
	v_mov_b32_e32 v0, 0
	s_branch .LBB0_1071

; DI unsigned xb_ld(unsigned* p) { return __hip_atomic_load(p, __ATOMIC_RELAXED, __HIP_MEMORY_SCOPE_AGENT); }
; #define XB_SPIN(cond, bar) do { unsigned _sp = 0; while (cond) { __builtin_amdgcn_s_sleep(1); \
;     if ((++_sp & 255u) == 0u) { if (xb_ld(&(bar)[XB_TMO])) break; if (_sp > XB_SPIN_CAP) { atomicAdd(&(bar)[XB_TMO], 1u); break; } } } } while (0)
; DI void xcd_barrier(const XcdBarrier& b) {
;     ...
;       XB_SPIN(xb_ld(&bar[XB_XGEN(b.x)]) == gen, bar);
.LBB0_1075:
	global_load_dword v231, v0, s[26:27] sc1
	s_add_i32 s0, s0, 1
	s_mov_b64 s[36:37], -1
	s_waitcnt vmcnt(3)
	v_cmp_ne_u32_e32 vcc, v231, v1
	s_orn2_b64 s[34:35], vcc, exec
	s_branch .LBB0_1070

; DI unsigned xb_ld(unsigned* p) { return __hip_atomic_load(p, __ATOMIC_RELAXED, __HIP_MEMORY_SCOPE_AGENT); }
; #define XB_SPIN(cond, bar) do { unsigned _sp = 0; while (cond) { __builtin_amdgcn_s_sleep(1); \
;     if ((++_sp & 255u) == 0u) { if (xb_ld(&(bar)[XB_TMO])) break; if (_sp > XB_SPIN_CAP) { atomicAdd(&(bar)[XB_TMO], 1u); break; } } } } while (0)
; DI void xcd_barrier(const XcdBarrier& b) {
;     ...
;       XB_SPIN(xb_ld(&bar[XB_XGEN(b.x)]) == gen, bar);
;       __builtin_amdgcn_fence(__ATOMIC_ACQUIRE, "agent");
;       asm volatile("s_waitcnt vmcnt(0)" ::: "memory");
.LBB0_1080:
	s_or_b64 exec, exec, s[22:23]
	s_waitcnt vmcnt(3)
	s_waitcnt vmcnt(3)

; DI unsigned xb_ld(unsigned* p) { return __hip_atomic_load(p, __ATOMIC_RELAXED, __HIP_MEMORY_SCOPE_AGENT); }
; DI unsigned xb_add(unsigned* p, unsigned v) { return __hip_atomic_fetch_add(p, v, __ATOMIC_RELAXED, __HIP_MEMORY_SCOPE_AGENT); }
; #define XB_SPIN(cond, bar) do { unsigned _sp = 0; while (cond) { __builtin_amdgcn_s_sleep(1); \
;     if ((++_sp & 255u) == 0u) { if (xb_ld(&(bar)[XB_TMO])) break; if (_sp > XB_SPIN_CAP) { atomicAdd(&(bar)[XB_TMO], 1u); break; } } } } while (0)
; DI void xcd_barrier(const XcdBarrier& b) {
;     ...
;     if (old + 1u == (gen + 1u) * nloc) {
;       __builtin_amdgcn_fence(__ATOMIC_RELEASE, "agent");
;       asm volatile("s_waitcnt vmcnt(0)" ::: "memory");
;       const unsigned og = xb_add(&bar[XB_TOP], 1u);
;       const unsigned tg = og / nx;
;       if (og + 1u == (tg + 1u) * nx) xb_add(&bar[XB_TOPGEN], 1u);
;       else XB_SPIN(xb_ld(&bar[XB_TOPGEN]) == tg, bar);
.LBB0_1084:
	s_or_b64 exec, exec, s[22:23]
	v_cvt_f32_u32_e32 v3, v0
	s_waitcnt vmcnt(0)
	v_readfirstlane_b32 s0, v2
	s_add_u32 s22, s86, 0xe7c4500
	s_addc_u32 s23, s87, 0
	v_rcp_iflag_f32_e32 v3, v3
	v_add_u32_e32 v1, s0, v1
	v_add_u32_e32 v4, 1, v1
	s_mov_b64 s[24:25], -1
	v_mul_f32_e32 v2, 0x4f7ffffe, v3
	v_cvt_u32_f32_e32 v2, v2
	v_sub_u32_e32 v3, 0, v0
	v_mul_lo_u32 v3, v3, v2
	v_mul_hi_u32 v3, v2, v3
	v_add_u32_e32 v2, v2, v3
	v_mul_hi_u32 v2, v1, v2
	v_mul_lo_u32 v3, v2, v0
	v_sub_u32_e32 v1, v1, v3
	v_add_u32_e32 v5, 1, v2
	v_cmp_ge_u32_e32 vcc, v1, v0
	v_sub_u32_e32 v3, v1, v0
	s_nop 0
	v_cndmask_b32_e32 v2, v2, v5, vcc
	v_cndmask_b32_e32 v1, v1, v3, vcc
	v_add_u32_e32 v3, 1, v2
	v_cmp_ge_u32_e32 vcc, v1, v0
	s_nop 1
	v_cndmask_b32_e32 v2, v2, v3, vcc
	v_mul_lo_u32 v1, v0, v2
	v_add_u32_e32 v0, v1, v0
	v_cmp_ne_u32_e32 vcc, v4, v0
	v_mov_b32_e32 v232, v0
	v_mov_b64_e32 v[0:1], s[22:23]
	s_and_saveexec_b64 s[16:17], vcc
	s_cbranch_execz .LBB0_1096
	v_mov_b32_e32 v0, 0
	v_mov_b32_e32 v233, 0xe7c4000
	global_load_dword v1, v233, s[86:87] offset:1024 sc1
	s_mov_b64 s[28:29], 0
	s_waitcnt vmcnt(0)
	v_cmp_lt_u32_e32 vcc, v1, v232
	v_mov_b32_e32 v231, v1
	s_and_saveexec_b64 s[26:27], vcc
	s_cbranch_execz .LBB0_1095
	s_add_u32 s24, s86, 0xe7c1200
	s_addc_u32 s25, s87, 0
	s_mov_b32 s0, 1
	s_branch .LBB0_1088

; DI unsigned xb_ld(unsigned* p) { return __hip_atomic_load(p, __ATOMIC_RELAXED, __HIP_MEMORY_SCOPE_AGENT); }
; #define XB_SPIN(cond, bar) do { unsigned _sp = 0; while (cond) { __builtin_amdgcn_s_sleep(1); \
;     if ((++_sp & 255u) == 0u) { if (xb_ld(&(bar)[XB_TMO])) break; if (_sp > XB_SPIN_CAP) { atomicAdd(&(bar)[XB_TMO], 1u); break; } } } } while (0)
; DI void xcd_barrier(const XcdBarrier& b) {
;     ...
;       else XB_SPIN(xb_ld(&bar[XB_TOPGEN]) == tg, bar);
.LBB0_1092:
	global_load_dword v231, v233, s[86:87] offset:1024 sc1
	s_add_i32 s0, s0, 1
	s_mov_b64 s[34:35], -1
	s_waitcnt vmcnt(3)
	v_cmp_ge_u32_e32 vcc, v231, v232
	s_orn2_b64 s[42:43], vcc, exec
	s_branch .LBB0_1087

; DI unsigned xb_add(unsigned* p, unsigned v) { return __hip_atomic_fetch_add(p, v, __ATOMIC_RELAXED, __HIP_MEMORY_SCOPE_AGENT); }
; DI void xcd_barrier(const XcdBarrier& b) {
;     ...
;       __builtin_amdgcn_fence(__ATOMIC_ACQUIRE, "agent");
;       xb_add(&bar[XB_XGEN(b.x)], 1u);
;       asm volatile("s_waitcnt vmcnt(0)" ::: "memory");
.LBB0_1098:
	s_or_b64 exec, exec, s[16:17]
	s_mov_b64 s[16:17], exec
	v_mbcnt_lo_u32_b32 v0, s16, 0
	v_mbcnt_hi_u32_b32 v0, s17, v0
	v_cmp_eq_u32_e32 vcc, 0, v0
	s_waitcnt vmcnt(3)
	s_and_saveexec_b64 s[22:23], vcc
	s_cbranch_execz .LBB0_1100
	s_bcnt1_i32_b64 s0, s[16:17]
	v_mov_b32_e32 v0, 0x2000
	v_mov_b32_e32 v1, s0
	global_atomic_add v0, v1, s[14:15] offset:1024
.LBB0_1100:
	s_or_b64 exec, exec, s[22:23]
	s_waitcnt vmcnt(3)

; DI unsigned xb_ld(unsigned* p) { return __hip_atomic_load(p, __ATOMIC_RELAXED, __HIP_MEMORY_SCOPE_AGENT); }
; DI unsigned xb_add(unsigned* p, unsigned v) { return __hip_atomic_fetch_add(p, v, __ATOMIC_RELAXED, __HIP_MEMORY_SCOPE_AGENT); }
; #define XB_SPIN(cond, bar) do { unsigned _sp = 0; while (cond) { __builtin_amdgcn_s_sleep(1); \
;     if ((++_sp & 255u) == 0u) { if (xb_ld(&(bar)[XB_TMO])) break; if (_sp > XB_SPIN_CAP) { atomicAdd(&(bar)[XB_TMO], 1u); break; } } } } while (0)
; DI void xcd_barrier(const XcdBarrier& b) {
;     ...
;     const unsigned old = xb_add(&bar[XB_XSUB(b.x)], 1u);
;     const unsigned gen = old / nloc;
;     if (old + 1u == (gen + 1u) * nloc) {
;       __builtin_amdgcn_fence(__ATOMIC_RELEASE, "agent");
;       asm volatile("s_waitcnt vmcnt(0)" ::: "memory");
;       const unsigned og = xb_add(&bar[XB_TOP], 1u);
;       const unsigned tg = og / nx;
;       if (og + 1u == (tg + 1u) * nx) xb_add(&bar[XB_TOPGEN], 1u);
;       else XB_SPIN(xb_ld(&bar[XB_TOPGEN]) == tg, bar);
;       __builtin_amdgcn_fence(__ATOMIC_ACQUIRE, "agent");
;       xb_add(&bar[XB_XGEN(b.x)], 1u);
;       asm volatile("s_waitcnt vmcnt(0)" ::: "memory");
;     } else {
;       XB_SPIN(xb_ld(&bar[XB_XGEN(b.x)]) == gen, bar);
.LBB0_1136:
	s_or_b64 exec, exec, s[12:13]
	v_cvt_f32_u32_e32 v4, v2
	s_waitcnt vmcnt(0)
	v_readfirstlane_b32 s0, v3
	buffer_inv sc1
	v_sub_u32_e32 v3, 0, v2
	v_rcp_iflag_f32_e32 v4, v4
	v_add_u32_e32 v5, s0, v1
	v_mul_f32_e32 v4, 0x4f7ffffe, v4
	v_cvt_u32_f32_e32 v4, v4
	v_mul_lo_u32 v1, v3, v4
	v_mul_hi_u32 v1, v4, v1
	v_add_u32_e32 v1, v4, v1
	v_mul_hi_u32 v1, v5, v1
	v_mul_lo_u32 v3, v1, v2
	v_sub_u32_e32 v3, v5, v3
	v_add_u32_e32 v4, 1, v1
	v_cmp_ge_u32_e32 vcc, v3, v2
	s_nop 1
	v_cndmask_b32_e32 v1, v1, v4, vcc
	v_sub_u32_e32 v4, v3, v2
	v_cndmask_b32_e32 v3, v3, v4, vcc
	v_add_u32_e32 v4, 1, v1
	v_cmp_ge_u32_e32 vcc, v3, v2
	v_add_u32_e32 v3, 1, v5
	s_nop 0
	v_cndmask_b32_e32 v1, v1, v4, vcc
	v_mul_lo_u32 v4, v2, v1
	v_add_u32_e32 v2, v4, v2
	v_cmp_ne_u32_e32 vcc, v3, v2
	s_and_saveexec_b64 s[0:1], vcc
	s_xor_b64 s[10:11], exec, s[0:1]
	s_cbranch_execz .LBB0_1150
	s_waitcnt lgkmcnt(0)
	v_mov_b32_e32 v0, 0x2000
	global_load_dword v0, v0, s[8:9] offset:1024 sc1
	s_add_u32 s16, s8, 0x2400
	s_addc_u32 s17, s9, 0
	s_waitcnt vmcnt(0)
	v_cmp_eq_u32_e32 vcc, v0, v1
	v_mov_b32_e32 v231, v1
	s_and_saveexec_b64 s[12:13], vcc
	s_cbranch_execz .LBB0_1149
	s_add_u32 s14, s86, 0xe7c1200
	s_addc_u32 s15, s87, 0
	s_mov_b32 s0, 1
	s_mov_b64 s[22:23], 0
	v_mov_b32_e32 v0, 0
	s_branch .LBB0_1140

; DI unsigned xb_ld(unsigned* p) { return __hip_atomic_load(p, __ATOMIC_RELAXED, __HIP_MEMORY_SCOPE_AGENT); }
; #define XB_SPIN(cond, bar) do { unsigned _sp = 0; while (cond) { __builtin_amdgcn_s_sleep(1); \
;     if ((++_sp & 255u) == 0u) { if (xb_ld(&(bar)[XB_TMO])) break; if (_sp > XB_SPIN_CAP) { atomicAdd(&(bar)[XB_TMO], 1u); break; } } } } while (0)
; DI void xcd_barrier(const XcdBarrier& b) {
;     ...
;       XB_SPIN(xb_ld(&bar[XB_XGEN(b.x)]) == gen, bar);
.LBB0_1144:
	global_load_dword v231, v0, s[16:17] sc1
	s_add_i32 s0, s0, 1
	s_mov_b64 s[28:29], -1
	s_waitcnt vmcnt(3)
	v_cmp_ne_u32_e32 vcc, v231, v1
	s_orn2_b64 s[26:27], vcc, exec
	s_branch .LBB0_1139

; DI unsigned xb_ld(unsigned* p) { return __hip_atomic_load(p, __ATOMIC_RELAXED, __HIP_MEMORY_SCOPE_AGENT); }
; DI unsigned xb_add(unsigned* p, unsigned v) { return __hip_atomic_fetch_add(p, v, __ATOMIC_RELAXED, __HIP_MEMORY_SCOPE_AGENT); }
; #define XB_SPIN(cond, bar) do { unsigned _sp = 0; while (cond) { __builtin_amdgcn_s_sleep(1); \
;     if ((++_sp & 255u) == 0u) { if (xb_ld(&(bar)[XB_TMO])) break; if (_sp > XB_SPIN_CAP) { atomicAdd(&(bar)[XB_TMO], 1u); break; } } } } while (0)
; DI void xcd_barrier(const XcdBarrier& b) {
;     ...
;     const unsigned old = xb_add(&bar[XB_XSUB(b.x)], 1u);
;     const unsigned gen = old / nloc;
;     if (old + 1u == (gen + 1u) * nloc) {
;       __builtin_amdgcn_fence(__ATOMIC_RELEASE, "agent");
;       asm volatile("s_waitcnt vmcnt(0)" ::: "memory");
;       const unsigned og = xb_add(&bar[XB_TOP], 1u);
;       const unsigned tg = og / nx;
;       if (og + 1u == (tg + 1u) * nx) xb_add(&bar[XB_TOPGEN], 1u);
;       else XB_SPIN(xb_ld(&bar[XB_TOPGEN]) == tg, bar);
.LBB0_1153:
	s_or_b64 exec, exec, s[12:13]
	v_cvt_f32_u32_e32 v3, v0
	s_waitcnt vmcnt(0)
	v_readfirstlane_b32 s0, v2
	s_add_u32 s12, s86, 0xe7c4500
	s_addc_u32 s13, s87, 0
	v_rcp_iflag_f32_e32 v3, v3
	v_add_u32_e32 v1, s0, v1
	v_add_u32_e32 v4, 1, v1
	s_mov_b64 s[14:15], -1
	v_mul_f32_e32 v2, 0x4f7ffffe, v3
	v_cvt_u32_f32_e32 v2, v2
	v_sub_u32_e32 v3, 0, v0
	v_mul_lo_u32 v3, v3, v2
	v_mul_hi_u32 v3, v2, v3
	v_add_u32_e32 v2, v2, v3
	v_mul_hi_u32 v2, v1, v2
	v_mul_lo_u32 v3, v2, v0
	v_sub_u32_e32 v1, v1, v3
	v_add_u32_e32 v5, 1, v2
	v_cmp_ge_u32_e32 vcc, v1, v0
	v_sub_u32_e32 v3, v1, v0
	s_nop 0
	v_cndmask_b32_e32 v2, v2, v5, vcc
	v_cndmask_b32_e32 v1, v1, v3, vcc
	v_add_u32_e32 v3, 1, v2
	v_cmp_ge_u32_e32 vcc, v1, v0
	s_nop 1
	v_cndmask_b32_e32 v2, v2, v3, vcc
	v_mul_lo_u32 v1, v0, v2
	v_add_u32_e32 v0, v1, v0
	v_cmp_ne_u32_e32 vcc, v4, v0
	v_mov_b32_e32 v232, v0
	v_mov_b64_e32 v[0:1], s[12:13]
	s_and_saveexec_b64 s[10:11], vcc
	s_cbranch_execz .LBB0_1165
	v_mov_b32_e32 v0, 0
	v_mov_b32_e32 v233, 0xe7c4000
	global_load_dword v1, v233, s[86:87] offset:1024 sc1
	s_mov_b64 s[22:23], 0
	s_waitcnt vmcnt(0)
	v_cmp_lt_u32_e32 vcc, v1, v232
	v_mov_b32_e32 v231, v1
	s_and_saveexec_b64 s[16:17], vcc
	s_cbranch_execz .LBB0_1164
	s_add_u32 s14, s86, 0xe7c1200
	s_addc_u32 s15, s87, 0
	s_mov_b32 s0, 1
	s_branch .LBB0_1157

; DI unsigned xb_ld(unsigned* p) { return __hip_atomic_load(p, __ATOMIC_RELAXED, __HIP_MEMORY_SCOPE_AGENT); }
; DI unsigned xb_add(unsigned* p, unsigned v) { return __hip_atomic_fetch_add(p, v, __ATOMIC_RELAXED, __HIP_MEMORY_SCOPE_AGENT); }
; #define XB_SPIN(cond, bar) do { unsigned _sp = 0; while (cond) { __builtin_amdgcn_s_sleep(1); \
;     if ((++_sp & 255u) == 0u) { if (xb_ld(&(bar)[XB_TMO])) break; if (_sp > XB_SPIN_CAP) { atomicAdd(&(bar)[XB_TMO], 1u); break; } } } } while (0)
; DI void xcd_barrier(const XcdBarrier& b) {
;     ...
;       const unsigned og = xb_add(&bar[XB_TOP], 1u);
;       const unsigned tg = og / nx;
;       if (og + 1u == (tg + 1u) * nx) xb_add(&bar[XB_TOPGEN], 1u);
;       else XB_SPIN(xb_ld(&bar[XB_TOPGEN]) == tg, bar);
.LBB0_1161:
	global_load_dword v231, v233, s[86:87] offset:1024 sc1
	s_add_i32 s0, s0, 1
	s_mov_b64 s[26:27], -1
	s_waitcnt vmcnt(3)
	v_cmp_ge_u32_e32 vcc, v231, v232
	s_orn2_b64 s[30:31], vcc, exec
	s_branch .LBB0_1156

; DI unsigned xb_ld(unsigned* p) { return __hip_atomic_load(p, __ATOMIC_RELAXED, __HIP_MEMORY_SCOPE_AGENT); }
; DI unsigned xb_add(unsigned* p, unsigned v) { return __hip_atomic_fetch_add(p, v, __ATOMIC_RELAXED, __HIP_MEMORY_SCOPE_AGENT); }
; #define XB_SPIN(cond, bar) do { unsigned _sp = 0; while (cond) { __builtin_amdgcn_s_sleep(1); \
;     if ((++_sp & 255u) == 0u) { if (xb_ld(&(bar)[XB_TMO])) break; if (_sp > XB_SPIN_CAP) { atomicAdd(&(bar)[XB_TMO], 1u); break; } } } } while (0)
; DI void xcd_barrier(const XcdBarrier& b) {
;     ...
;     const unsigned old = xb_add(&bar[XB_XSUB(b.x)], 1u);
;     const unsigned gen = old / nloc;
;     if (old + 1u == (gen + 1u) * nloc) {
;       __builtin_amdgcn_fence(__ATOMIC_RELEASE, "agent");
;       asm volatile("s_waitcnt vmcnt(0)" ::: "memory");
;       const unsigned og = xb_add(&bar[XB_TOP], 1u);
;       const unsigned tg = og / nx;
;       if (og + 1u == (tg + 1u) * nx) xb_add(&bar[XB_TOPGEN], 1u);
;       else XB_SPIN(xb_ld(&bar[XB_TOPGEN]) == tg, bar);
;       __builtin_amdgcn_fence(__ATOMIC_ACQUIRE, "agent");
;       xb_add(&bar[XB_XGEN(b.x)], 1u);
;       asm volatile("s_waitcnt vmcnt(0)" ::: "memory");
;     } else {
;       XB_SPIN(xb_ld(&bar[XB_XGEN(b.x)]) == gen, bar);
.LBB0_1193:
	s_or_b64 exec, exec, s[10:11]
	v_cvt_f32_u32_e32 v4, v2
	s_waitcnt vmcnt(0)
	v_readfirstlane_b32 s0, v3
	buffer_inv sc1
	v_sub_u32_e32 v3, 0, v2
	v_rcp_iflag_f32_e32 v4, v4
	v_add_u32_e32 v5, s0, v1
	v_mul_f32_e32 v4, 0x4f7ffffe, v4
	v_cvt_u32_f32_e32 v4, v4
	v_mul_lo_u32 v1, v3, v4
	v_mul_hi_u32 v1, v4, v1
	v_add_u32_e32 v1, v4, v1
	v_mul_hi_u32 v1, v5, v1
	v_mul_lo_u32 v3, v1, v2
	v_sub_u32_e32 v3, v5, v3
	v_add_u32_e32 v4, 1, v1
	v_cmp_ge_u32_e32 vcc, v3, v2
	s_nop 1
	v_cndmask_b32_e32 v1, v1, v4, vcc
	v_sub_u32_e32 v4, v3, v2
	v_cndmask_b32_e32 v3, v3, v4, vcc
	v_add_u32_e32 v4, 1, v1
	v_cmp_ge_u32_e32 vcc, v3, v2
	v_add_u32_e32 v3, 1, v5
	s_nop 0
	v_cndmask_b32_e32 v1, v1, v4, vcc
	v_mul_lo_u32 v4, v2, v1
	v_add_u32_e32 v2, v4, v2
	v_cmp_ne_u32_e32 vcc, v3, v2
	s_and_saveexec_b64 s[0:1], vcc
	s_xor_b64 s[8:9], exec, s[0:1]
	s_cbranch_execz .LBB0_1207
	s_waitcnt lgkmcnt(0)
	v_mov_b32_e32 v0, 0x2000
	global_load_dword v0, v0, s[6:7] offset:1024 sc1
	s_add_u32 s14, s6, 0x2400
	s_addc_u32 s15, s7, 0
	s_waitcnt vmcnt(0)
	v_cmp_eq_u32_e32 vcc, v0, v1
	v_mov_b32_e32 v231, v1
	s_and_saveexec_b64 s[10:11], vcc
	s_cbranch_execz .LBB0_1206
	s_add_u32 s12, s86, 0xe7c1200
	s_addc_u32 s13, s87, 0
	s_mov_b32 s0, 1
	s_mov_b64 s[16:17], 0
	v_mov_b32_e32 v0, 0
	s_branch .LBB0_1197

; DI unsigned xb_ld(unsigned* p) { return __hip_atomic_load(p, __ATOMIC_RELAXED, __HIP_MEMORY_SCOPE_AGENT); }
; #define XB_SPIN(cond, bar) do { unsigned _sp = 0; while (cond) { __builtin_amdgcn_s_sleep(1); \
;     if ((++_sp & 255u) == 0u) { if (xb_ld(&(bar)[XB_TMO])) break; if (_sp > XB_SPIN_CAP) { atomicAdd(&(bar)[XB_TMO], 1u); break; } } } } while (0)
; DI void xcd_barrier(const XcdBarrier& b) {
;     ...
;       XB_SPIN(xb_ld(&bar[XB_XGEN(b.x)]) == gen, bar);
;       __builtin_amdgcn_fence(__ATOMIC_ACQUIRE, "agent");
;       asm volatile("s_waitcnt vmcnt(0)" ::: "memory");
.LBB0_1201:
	global_load_dword v231, v0, s[14:15] sc1
	s_add_i32 s0, s0, 1
	s_mov_b64 s[24:25], -1
	s_waitcnt vmcnt(3)
	v_cmp_ne_u32_e32 vcc, v231, v1
	s_orn2_b64 s[22:23], vcc, exec
	s_branch .LBB0_1196

; DI unsigned xb_ld(unsigned* p) { return __hip_atomic_load(p, __ATOMIC_RELAXED, __HIP_MEMORY_SCOPE_AGENT); }
; #define XB_SPIN(cond, bar) do { unsigned _sp = 0; while (cond) { __builtin_amdgcn_s_sleep(1); \
;     if ((++_sp & 255u) == 0u) { if (xb_ld(&(bar)[XB_TMO])) break; if (_sp > XB_SPIN_CAP) { atomicAdd(&(bar)[XB_TMO], 1u); break; } } } } while (0)
; DI void xcd_barrier(const XcdBarrier& b) {
;     ...
;       XB_SPIN(xb_ld(&bar[XB_XGEN(b.x)]) == gen, bar);
;       __builtin_amdgcn_fence(__ATOMIC_ACQUIRE, "agent");
;       asm volatile("s_waitcnt vmcnt(0)" ::: "memory");
.LBB0_1206:
	s_or_b64 exec, exec, s[10:11]
	s_waitcnt vmcnt(3)
	s_waitcnt vmcnt(3)

; DI unsigned xb_ld(unsigned* p) { return __hip_atomic_load(p, __ATOMIC_RELAXED, __HIP_MEMORY_SCOPE_AGENT); }
; DI unsigned xb_add(unsigned* p, unsigned v) { return __hip_atomic_fetch_add(p, v, __ATOMIC_RELAXED, __HIP_MEMORY_SCOPE_AGENT); }
; #define XB_SPIN(cond, bar) do { unsigned _sp = 0; while (cond) { __builtin_amdgcn_s_sleep(1); \
;     if ((++_sp & 255u) == 0u) { if (xb_ld(&(bar)[XB_TMO])) break; if (_sp > XB_SPIN_CAP) { atomicAdd(&(bar)[XB_TMO], 1u); break; } } } } while (0)
; DI void xcd_barrier(const XcdBarrier& b) {
;     ...
;     const unsigned old = xb_add(&bar[XB_XSUB(b.x)], 1u);
;     const unsigned gen = old / nloc;
;     if (old + 1u == (gen + 1u) * nloc) {
;       __builtin_amdgcn_fence(__ATOMIC_RELEASE, "agent");
;       asm volatile("s_waitcnt vmcnt(0)" ::: "memory");
;       const unsigned og = xb_add(&bar[XB_TOP], 1u);
;       const unsigned tg = og / nx;
;       if (og + 1u == (tg + 1u) * nx) xb_add(&bar[XB_TOPGEN], 1u);
;       else XB_SPIN(xb_ld(&bar[XB_TOPGEN]) == tg, bar);
.LBB0_1210:
	s_or_b64 exec, exec, s[10:11]
	v_cvt_f32_u32_e32 v3, v0
	s_waitcnt vmcnt(0)
	v_readfirstlane_b32 s0, v2
	s_add_u32 s10, s86, 0xe7c4500
	s_addc_u32 s11, s87, 0
	v_rcp_iflag_f32_e32 v3, v3
	v_add_u32_e32 v1, s0, v1
	v_add_u32_e32 v4, 1, v1
	s_mov_b64 s[12:13], -1
	v_mul_f32_e32 v2, 0x4f7ffffe, v3
	v_cvt_u32_f32_e32 v2, v2
	v_sub_u32_e32 v3, 0, v0
	v_mul_lo_u32 v3, v3, v2
	v_mul_hi_u32 v3, v2, v3
	v_add_u32_e32 v2, v2, v3
	v_mul_hi_u32 v2, v1, v2
	v_mul_lo_u32 v3, v2, v0
	v_sub_u32_e32 v1, v1, v3
	v_add_u32_e32 v5, 1, v2
	v_cmp_ge_u32_e32 vcc, v1, v0
	v_sub_u32_e32 v3, v1, v0
	s_nop 0
	v_cndmask_b32_e32 v2, v2, v5, vcc
	v_cndmask_b32_e32 v1, v1, v3, vcc
	v_add_u32_e32 v3, 1, v2
	v_cmp_ge_u32_e32 vcc, v1, v0
	s_nop 1
	v_cndmask_b32_e32 v2, v2, v3, vcc
	v_mul_lo_u32 v1, v0, v2
	v_add_u32_e32 v0, v1, v0
	v_cmp_ne_u32_e32 vcc, v4, v0
	v_mov_b32_e32 v232, v0
	v_mov_b64_e32 v[0:1], s[10:11]
	s_and_saveexec_b64 s[8:9], vcc
	s_cbranch_execz .LBB0_1222
	v_mov_b32_e32 v0, 0
	v_mov_b32_e32 v233, 0xe7c4000
	global_load_dword v1, v233, s[86:87] offset:1024 sc1
	s_mov_b64 s[16:17], 0
	s_waitcnt vmcnt(0)
	v_cmp_lt_u32_e32 vcc, v1, v232
	v_mov_b32_e32 v231, v1
	s_and_saveexec_b64 s[14:15], vcc
	s_cbranch_execz .LBB0_1221
	s_add_u32 s12, s86, 0xe7c1200
	s_addc_u32 s13, s87, 0
	s_mov_b32 s0, 1
	s_branch .LBB0_1214

; DI unsigned xb_ld(unsigned* p) { return __hip_atomic_load(p, __ATOMIC_RELAXED, __HIP_MEMORY_SCOPE_AGENT); }
; DI unsigned xb_add(unsigned* p, unsigned v) { return __hip_atomic_fetch_add(p, v, __ATOMIC_RELAXED, __HIP_MEMORY_SCOPE_AGENT); }
; #define XB_SPIN(cond, bar) do { unsigned _sp = 0; while (cond) { __builtin_amdgcn_s_sleep(1); \
;     if ((++_sp & 255u) == 0u) { if (xb_ld(&(bar)[XB_TMO])) break; if (_sp > XB_SPIN_CAP) { atomicAdd(&(bar)[XB_TMO], 1u); break; } } } } while (0)
; DI void xcd_barrier(const XcdBarrier& b) {
;     ...
;       const unsigned og = xb_add(&bar[XB_TOP], 1u);
;       const unsigned tg = og / nx;
;       if (og + 1u == (tg + 1u) * nx) xb_add(&bar[XB_TOPGEN], 1u);
;       else XB_SPIN(xb_ld(&bar[XB_TOPGEN]) == tg, bar);
.LBB0_1218:
	global_load_dword v231, v233, s[86:87] offset:1024 sc1
	s_add_i32 s0, s0, 1
	s_mov_b64 s[22:23], -1
	s_waitcnt vmcnt(3)
	v_cmp_ge_u32_e32 vcc, v231, v232
	s_orn2_b64 s[26:27], vcc, exec
	s_branch .LBB0_1213

; DI unsigned xb_add(unsigned* p, unsigned v) { return __hip_atomic_fetch_add(p, v, __ATOMIC_RELAXED, __HIP_MEMORY_SCOPE_AGENT); }
; DI void xcd_barrier(const XcdBarrier& b) {
;     ...
;       __builtin_amdgcn_fence(__ATOMIC_ACQUIRE, "agent");
;       xb_add(&bar[XB_XGEN(b.x)], 1u);
;       asm volatile("s_waitcnt vmcnt(0)" ::: "memory");
.LBB0_1224:
	s_or_b64 exec, exec, s[8:9]
	s_mov_b64 s[8:9], exec
	v_mbcnt_lo_u32_b32 v0, s8, 0
	v_mbcnt_hi_u32_b32 v0, s9, v0
	v_cmp_eq_u32_e32 vcc, 0, v0
	s_waitcnt vmcnt(3)
	s_and_saveexec_b64 s[10:11], vcc
	s_cbranch_execz .LBB0_1226
	s_bcnt1_i32_b64 s0, s[8:9]
	v_mov_b32_e32 v0, 0x2000
	v_mov_b32_e32 v1, s0
	global_atomic_add v0, v1, s[6:7] offset:1024
.LBB0_1226:
	s_or_b64 exec, exec, s[10:11]
	s_waitcnt vmcnt(3)

; DI unsigned xb_ld(unsigned* p) { return __hip_atomic_load(p, __ATOMIC_RELAXED, __HIP_MEMORY_SCOPE_AGENT); }
; #define XB_SPIN(cond, bar) do { unsigned _sp = 0; while (cond) { __builtin_amdgcn_s_sleep(1); \
;     if ((++_sp & 255u) == 0u) { if (xb_ld(&(bar)[XB_TMO])) break; if (_sp > XB_SPIN_CAP) { atomicAdd(&(bar)[XB_TMO], 1u); break; } } } } while (0)
; DI void xcd_barrier(const XcdBarrier& b) {
;     ...
;       XB_SPIN(xb_ld(&bar[XB_XGEN(b.x)]) == gen, bar);
;       __builtin_amdgcn_fence(__ATOMIC_ACQUIRE, "agent");
;       asm volatile("s_waitcnt vmcnt(0)" ::: "memory");
.LBB0_1325:
	global_load_dword v231, v0, s[14:15] sc1
	s_add_i32 s0, s0, 1
	s_mov_b64 s[22:23], -1
	s_waitcnt vmcnt(3)
	v_cmp_ne_u32_e32 vcc, v231, v1
	s_orn2_b64 s[20:21], vcc, exec
	s_branch .LBB0_1320

; DI unsigned xb_ld(unsigned* p) { return __hip_atomic_load(p, __ATOMIC_RELAXED, __HIP_MEMORY_SCOPE_AGENT); }
; DI unsigned xb_add(unsigned* p, unsigned v) { return __hip_atomic_fetch_add(p, v, __ATOMIC_RELAXED, __HIP_MEMORY_SCOPE_AGENT); }
; #define XB_SPIN(cond, bar) do { unsigned _sp = 0; while (cond) { __builtin_amdgcn_s_sleep(1); \
;     if ((++_sp & 255u) == 0u) { if (xb_ld(&(bar)[XB_TMO])) break; if (_sp > XB_SPIN_CAP) { atomicAdd(&(bar)[XB_TMO], 1u); break; } } } } while (0)
; DI void xcd_barrier(const XcdBarrier& b) {
;     ...
;       const unsigned og = xb_add(&bar[XB_TOP], 1u);
;       const unsigned tg = og / nx;
;       if (og + 1u == (tg + 1u) * nx) xb_add(&bar[XB_TOPGEN], 1u);
;       else XB_SPIN(xb_ld(&bar[XB_TOPGEN]) == tg, bar);
.LBB0_1342:
	global_load_dword v231, v233, s[86:87] offset:1024 sc1
	s_add_i32 s0, s0, 1
	s_mov_b64 s[20:21], -1
	s_waitcnt vmcnt(3)
	v_cmp_ge_u32_e32 vcc, v231, v232
	s_orn2_b64 s[24:25], vcc, exec
	s_branch .LBB0_1337

; DI unsigned xb_ld(unsigned* p) { return __hip_atomic_load(p, __ATOMIC_RELAXED, __HIP_MEMORY_SCOPE_AGENT); }
; DI unsigned xb_add(unsigned* p, unsigned v) { return __hip_atomic_fetch_add(p, v, __ATOMIC_RELAXED, __HIP_MEMORY_SCOPE_AGENT); }
; #define XB_SPIN(cond, bar) do { unsigned _sp = 0; while (cond) { __builtin_amdgcn_s_sleep(1); \
;     if ((++_sp & 255u) == 0u) { if (xb_ld(&(bar)[XB_TMO])) break; if (_sp > XB_SPIN_CAP) { atomicAdd(&(bar)[XB_TMO], 1u); break; } } } } while (0)
; DI void xcd_barrier(const XcdBarrier& b) {
;     ...
;     const unsigned old = xb_add(&bar[XB_XSUB(b.x)], 1u);
;     const unsigned gen = old / nloc;
;     if (old + 1u == (gen + 1u) * nloc) {
;       __builtin_amdgcn_fence(__ATOMIC_RELEASE, "agent");
;       asm volatile("s_waitcnt vmcnt(0)" ::: "memory");
;       const unsigned og = xb_add(&bar[XB_TOP], 1u);
;       const unsigned tg = og / nx;
;       if (og + 1u == (tg + 1u) * nx) xb_add(&bar[XB_TOPGEN], 1u);
;       else XB_SPIN(xb_ld(&bar[XB_TOPGEN]) == tg, bar);
;       __builtin_amdgcn_fence(__ATOMIC_ACQUIRE, "agent");
;       xb_add(&bar[XB_XGEN(b.x)], 1u);
;       asm volatile("s_waitcnt vmcnt(0)" ::: "memory");
;     } else {
;       XB_SPIN(xb_ld(&bar[XB_XGEN(b.x)]) == gen, bar);
.LBB0_1376:
	s_or_b64 exec, exec, s[12:13]
	v_cvt_f32_u32_e32 v4, v2
	s_waitcnt vmcnt(0)
	v_readfirstlane_b32 s2, v3
	buffer_inv sc1
	v_sub_u32_e32 v3, 0, v2
	v_rcp_iflag_f32_e32 v4, v4
	v_add_u32_e32 v5, s2, v1
	v_mul_f32_e32 v4, 0x4f7ffffe, v4
	v_cvt_u32_f32_e32 v4, v4
	v_mul_lo_u32 v1, v3, v4
	v_mul_hi_u32 v1, v4, v1
	v_add_u32_e32 v1, v4, v1
	v_mul_hi_u32 v1, v5, v1
	v_mul_lo_u32 v3, v1, v2
	v_sub_u32_e32 v3, v5, v3
	v_add_u32_e32 v4, 1, v1
	v_cmp_ge_u32_e32 vcc, v3, v2
	s_nop 1
	v_cndmask_b32_e32 v1, v1, v4, vcc
	v_sub_u32_e32 v4, v3, v2
	v_cndmask_b32_e32 v3, v3, v4, vcc
	v_add_u32_e32 v4, 1, v1
	v_cmp_ge_u32_e32 vcc, v3, v2
	v_add_u32_e32 v3, 1, v5
	s_nop 0
	v_cndmask_b32_e32 v1, v1, v4, vcc
	v_mul_lo_u32 v4, v2, v1
	v_add_u32_e32 v2, v4, v2
	v_cmp_ne_u32_e32 vcc, v3, v2
	s_and_saveexec_b64 s[8:9], vcc
	s_xor_b64 s[8:9], exec, s[8:9]
	s_cbranch_execz .LBB0_1390
	s_waitcnt lgkmcnt(0)
	v_mov_b32_e32 v0, 0x2000
	global_load_dword v0, v0, s[6:7] offset:1024 sc1
	s_add_u32 s16, s6, 0x2400
	s_addc_u32 s17, s7, 0
	s_waitcnt vmcnt(0)
	v_cmp_eq_u32_e32 vcc, v0, v1
	v_mov_b32_e32 v231, v1
	s_and_saveexec_b64 s[12:13], vcc
	s_cbranch_execz .LBB0_1389
	s_add_u32 s14, s86, 0xe7c1200
	s_addc_u32 s15, s87, 0
	s_mov_b32 s3, 1
	s_mov_b64 s[18:19], 0
	v_mov_b32_e32 v0, 0
	s_branch .LBB0_1380

; DI unsigned xb_ld(unsigned* p) { return __hip_atomic_load(p, __ATOMIC_RELAXED, __HIP_MEMORY_SCOPE_AGENT); }
; #define XB_SPIN(cond, bar) do { unsigned _sp = 0; while (cond) { __builtin_amdgcn_s_sleep(1); \
;     if ((++_sp & 255u) == 0u) { if (xb_ld(&(bar)[XB_TMO])) break; if (_sp > XB_SPIN_CAP) { atomicAdd(&(bar)[XB_TMO], 1u); break; } } } } while (0)
; DI void xcd_barrier(const XcdBarrier& b) {
;     ...
;       XB_SPIN(xb_ld(&bar[XB_XGEN(b.x)]) == gen, bar);
;       __builtin_amdgcn_fence(__ATOMIC_ACQUIRE, "agent");
;       asm volatile("s_waitcnt vmcnt(0)" ::: "memory");
.LBB0_1384:
	global_load_dword v231, v0, s[16:17] sc1
	s_add_i32 s3, s3, 1
	s_mov_b64 s[24:25], -1
	s_waitcnt vmcnt(3)
	v_cmp_ne_u32_e32 vcc, v231, v1
	s_orn2_b64 s[22:23], vcc, exec
	s_branch .LBB0_1379

; DI unsigned xb_ld(unsigned* p) { return __hip_atomic_load(p, __ATOMIC_RELAXED, __HIP_MEMORY_SCOPE_AGENT); }
; DI unsigned xb_add(unsigned* p, unsigned v) { return __hip_atomic_fetch_add(p, v, __ATOMIC_RELAXED, __HIP_MEMORY_SCOPE_AGENT); }
; #define XB_SPIN(cond, bar) do { unsigned _sp = 0; while (cond) { __builtin_amdgcn_s_sleep(1); \
;     if ((++_sp & 255u) == 0u) { if (xb_ld(&(bar)[XB_TMO])) break; if (_sp > XB_SPIN_CAP) { atomicAdd(&(bar)[XB_TMO], 1u); break; } } } } while (0)
; DI void xcd_barrier(const XcdBarrier& b) {
;     ...
;     const unsigned old = xb_add(&bar[XB_XSUB(b.x)], 1u);
;     const unsigned gen = old / nloc;
;     if (old + 1u == (gen + 1u) * nloc) {
;       __builtin_amdgcn_fence(__ATOMIC_RELEASE, "agent");
;       asm volatile("s_waitcnt vmcnt(0)" ::: "memory");
;       const unsigned og = xb_add(&bar[XB_TOP], 1u);
;       const unsigned tg = og / nx;
;       if (og + 1u == (tg + 1u) * nx) xb_add(&bar[XB_TOPGEN], 1u);
;       else XB_SPIN(xb_ld(&bar[XB_TOPGEN]) == tg, bar);
.LBB0_1393:
	s_or_b64 exec, exec, s[12:13]
	v_cvt_f32_u32_e32 v3, v0
	s_waitcnt vmcnt(0)
	v_readfirstlane_b32 s2, v2
	s_add_u32 s12, s86, 0xe7c4500
	s_addc_u32 s13, s87, 0
	v_rcp_iflag_f32_e32 v3, v3
	v_add_u32_e32 v1, s2, v1
	v_add_u32_e32 v4, 1, v1
	s_mov_b64 s[14:15], -1
	v_mul_f32_e32 v2, 0x4f7ffffe, v3
	v_cvt_u32_f32_e32 v2, v2
	v_sub_u32_e32 v3, 0, v0
	v_mul_lo_u32 v3, v3, v2
	v_mul_hi_u32 v3, v2, v3
	v_add_u32_e32 v2, v2, v3
	v_mul_hi_u32 v2, v1, v2
	v_mul_lo_u32 v3, v2, v0
	v_sub_u32_e32 v1, v1, v3
	v_add_u32_e32 v5, 1, v2
	v_cmp_ge_u32_e32 vcc, v1, v0
	v_sub_u32_e32 v3, v1, v0
	s_nop 0
	v_cndmask_b32_e32 v2, v2, v5, vcc
	v_cndmask_b32_e32 v1, v1, v3, vcc
	v_add_u32_e32 v3, 1, v2
	v_cmp_ge_u32_e32 vcc, v1, v0
	s_nop 1
	v_cndmask_b32_e32 v2, v2, v3, vcc
	v_mul_lo_u32 v1, v0, v2
	v_add_u32_e32 v0, v1, v0
	v_cmp_ne_u32_e32 vcc, v4, v0
	v_mov_b32_e32 v232, v0
	v_mov_b64_e32 v[0:1], s[12:13]
	s_and_saveexec_b64 s[8:9], vcc
	s_cbranch_execz .LBB0_1405
	v_mov_b32_e32 v0, 0
	v_mov_b32_e32 v233, 0xe7c4000
	global_load_dword v1, v233, s[86:87] offset:1024 sc1
	s_mov_b64 s[18:19], 0
	s_waitcnt vmcnt(0)
	v_cmp_lt_u32_e32 vcc, v1, v232
	v_mov_b32_e32 v231, v1
	s_and_saveexec_b64 s[16:17], vcc
	s_cbranch_execz .LBB0_1404
	s_add_u32 s14, s86, 0xe7c1200
	s_addc_u32 s15, s87, 0
	s_mov_b32 s3, 1
	s_branch .LBB0_1397

; DI unsigned xb_ld(unsigned* p) { return __hip_atomic_load(p, __ATOMIC_RELAXED, __HIP_MEMORY_SCOPE_AGENT); }
; DI unsigned xb_add(unsigned* p, unsigned v) { return __hip_atomic_fetch_add(p, v, __ATOMIC_RELAXED, __HIP_MEMORY_SCOPE_AGENT); }
; #define XB_SPIN(cond, bar) do { unsigned _sp = 0; while (cond) { __builtin_amdgcn_s_sleep(1); \
;     if ((++_sp & 255u) == 0u) { if (xb_ld(&(bar)[XB_TMO])) break; if (_sp > XB_SPIN_CAP) { atomicAdd(&(bar)[XB_TMO], 1u); break; } } } } while (0)
; DI void xcd_barrier(const XcdBarrier& b) {
;     ...
;       const unsigned og = xb_add(&bar[XB_TOP], 1u);
;       const unsigned tg = og / nx;
;       if (og + 1u == (tg + 1u) * nx) xb_add(&bar[XB_TOPGEN], 1u);
;       else XB_SPIN(xb_ld(&bar[XB_TOPGEN]) == tg, bar);
.LBB0_1401:
	global_load_dword v231, v233, s[86:87] offset:1024 sc1
	s_add_i32 s3, s3, 1
	s_mov_b64 s[22:23], -1
	s_waitcnt vmcnt(3)
	v_cmp_ge_u32_e32 vcc, v231, v232
	s_orn2_b64 s[26:27], vcc, exec
	s_branch .LBB0_1396

; DI unsigned xb_add(unsigned* p, unsigned v) { return __hip_atomic_fetch_add(p, v, __ATOMIC_RELAXED, __HIP_MEMORY_SCOPE_AGENT); }
; DI void xcd_barrier(const XcdBarrier& b) {
;     ...
;       __builtin_amdgcn_fence(__ATOMIC_ACQUIRE, "agent");
;       xb_add(&bar[XB_XGEN(b.x)], 1u);
.LBB0_1407:
	s_or_b64 exec, exec, s[8:9]
	s_mov_b64 s[8:9], exec
	v_mbcnt_lo_u32_b32 v0, s8, 0
	v_mbcnt_hi_u32_b32 v0, s9, v0
	v_cmp_eq_u32_e32 vcc, 0, v0
	s_waitcnt vmcnt(3)
	s_and_saveexec_b64 s[12:13], vcc
	s_cbranch_execz .LBB0_1409
	s_bcnt1_i32_b64 s2, s[8:9]
	v_mov_b32_e32 v0, 0x2000
	v_mov_b32_e32 v1, s2
	global_atomic_add v0, v1, s[6:7] offset:1024

; DI unsigned xb_ld(unsigned* p) { return __hip_atomic_load(p, __ATOMIC_RELAXED, __HIP_MEMORY_SCOPE_AGENT); }
; DI unsigned xb_add(unsigned* p, unsigned v) { return __hip_atomic_fetch_add(p, v, __ATOMIC_RELAXED, __HIP_MEMORY_SCOPE_AGENT); }
; #define XB_SPIN(cond, bar) do { unsigned _sp = 0; while (cond) { __builtin_amdgcn_s_sleep(1); \
;     if ((++_sp & 255u) == 0u) { if (xb_ld(&(bar)[XB_TMO])) break; if (_sp > XB_SPIN_CAP) { atomicAdd(&(bar)[XB_TMO], 1u); break; } } } } while (0)
; DI void xcd_barrier(const XcdBarrier& b) {
;     ...
;     const unsigned old = xb_add(&bar[XB_XSUB(b.x)], 1u);
;     const unsigned gen = old / nloc;
;     if (old + 1u == (gen + 1u) * nloc) {
;       __builtin_amdgcn_fence(__ATOMIC_RELEASE, "agent");
;       asm volatile("s_waitcnt vmcnt(0)" ::: "memory");
;       const unsigned og = xb_add(&bar[XB_TOP], 1u);
;       const unsigned tg = og / nx;
;       if (og + 1u == (tg + 1u) * nx) xb_add(&bar[XB_TOPGEN], 1u);
;       else XB_SPIN(xb_ld(&bar[XB_TOPGEN]) == tg, bar);
;       __builtin_amdgcn_fence(__ATOMIC_ACQUIRE, "agent");
;       xb_add(&bar[XB_XGEN(b.x)], 1u);
;       asm volatile("s_waitcnt vmcnt(0)" ::: "memory");
;     } else {
;       XB_SPIN(xb_ld(&bar[XB_XGEN(b.x)]) == gen, bar);
.LBB0_1501:
	s_or_b64 exec, exec, s[6:7]
	v_cvt_f32_u32_e32 v4, v2
	s_waitcnt vmcnt(0)
	v_readfirstlane_b32 s4, v3
	buffer_inv sc1
	v_sub_u32_e32 v3, 0, v2
	v_rcp_iflag_f32_e32 v4, v4
	v_add_u32_e32 v5, s4, v1
	v_mul_f32_e32 v4, 0x4f7ffffe, v4
	v_cvt_u32_f32_e32 v4, v4
	v_mul_lo_u32 v1, v3, v4
	v_mul_hi_u32 v1, v4, v1
	v_add_u32_e32 v1, v4, v1
	v_mul_hi_u32 v1, v5, v1
	v_mul_lo_u32 v3, v1, v2
	v_sub_u32_e32 v3, v5, v3
	v_add_u32_e32 v4, 1, v1
	v_cmp_ge_u32_e32 vcc, v3, v2
	s_nop 1
	v_cndmask_b32_e32 v1, v1, v4, vcc
	v_sub_u32_e32 v4, v3, v2
	v_cndmask_b32_e32 v3, v3, v4, vcc
	v_add_u32_e32 v4, 1, v1
	v_cmp_ge_u32_e32 vcc, v3, v2
	v_add_u32_e32 v3, 1, v5
	s_nop 0
	v_cndmask_b32_e32 v1, v1, v4, vcc
	v_mul_lo_u32 v4, v2, v1
	v_add_u32_e32 v2, v4, v2
	v_cmp_ne_u32_e32 vcc, v3, v2
	s_and_saveexec_b64 s[4:5], vcc
	s_xor_b64 s[4:5], exec, s[4:5]
	s_cbranch_execz .LBB0_1515
	s_waitcnt lgkmcnt(0)
	v_mov_b32_e32 v0, 0x2000
	global_load_dword v0, v0, s[0:1] offset:1024 sc1
	s_add_u32 s10, s0, 0x2400
	s_addc_u32 s11, s1, 0
	s_waitcnt vmcnt(0)
	v_cmp_eq_u32_e32 vcc, v0, v1
	v_mov_b32_e32 v231, v1
	s_and_saveexec_b64 s[6:7], vcc
	s_cbranch_execz .LBB0_1514
	s_add_u32 s8, s86, 0xe7c1200
	s_addc_u32 s9, s87, 0
	s_mov_b32 s22, 1
	s_mov_b64 s[12:13], 0
	v_mov_b32_e32 v0, 0
	s_branch .LBB0_1505

; DI unsigned xb_ld(unsigned* p) { return __hip_atomic_load(p, __ATOMIC_RELAXED, __HIP_MEMORY_SCOPE_AGENT); }
; #define XB_SPIN(cond, bar) do { unsigned _sp = 0; while (cond) { __builtin_amdgcn_s_sleep(1); \
;     if ((++_sp & 255u) == 0u) { if (xb_ld(&(bar)[XB_TMO])) break; if (_sp > XB_SPIN_CAP) { atomicAdd(&(bar)[XB_TMO], 1u); break; } } } } while (0)
; DI void xcd_barrier(const XcdBarrier& b) {
;     ...
;       XB_SPIN(xb_ld(&bar[XB_XGEN(b.x)]) == gen, bar);
;       __builtin_amdgcn_fence(__ATOMIC_ACQUIRE, "agent");
;       asm volatile("s_waitcnt vmcnt(0)" ::: "memory");
.LBB0_1509:
	global_load_dword v231, v0, s[10:11] sc1
	s_add_i32 s22, s22, 1
	s_mov_b64 s[18:19], -1
	s_waitcnt vmcnt(3)
	v_cmp_ne_u32_e32 vcc, v231, v1
	s_orn2_b64 s[16:17], vcc, exec
	s_branch .LBB0_1504

; DI unsigned xb_ld(unsigned* p) { return __hip_atomic_load(p, __ATOMIC_RELAXED, __HIP_MEMORY_SCOPE_AGENT); }
; #define XB_SPIN(cond, bar) do { unsigned _sp = 0; while (cond) { __builtin_amdgcn_s_sleep(1); \
;     if ((++_sp & 255u) == 0u) { if (xb_ld(&(bar)[XB_TMO])) break; if (_sp > XB_SPIN_CAP) { atomicAdd(&(bar)[XB_TMO], 1u); break; } } } } while (0)
; DI void xcd_barrier(const XcdBarrier& b) {
;     ...
;       XB_SPIN(xb_ld(&bar[XB_XGEN(b.x)]) == gen, bar);
;       __builtin_amdgcn_fence(__ATOMIC_ACQUIRE, "agent");
;       asm volatile("s_waitcnt vmcnt(0)" ::: "memory");
.LBB0_1514:
	s_or_b64 exec, exec, s[6:7]
	s_waitcnt vmcnt(3)
	s_waitcnt vmcnt(3)

; DI unsigned xb_ld(unsigned* p) { return __hip_atomic_load(p, __ATOMIC_RELAXED, __HIP_MEMORY_SCOPE_AGENT); }
; DI unsigned xb_add(unsigned* p, unsigned v) { return __hip_atomic_fetch_add(p, v, __ATOMIC_RELAXED, __HIP_MEMORY_SCOPE_AGENT); }
; #define XB_SPIN(cond, bar) do { unsigned _sp = 0; while (cond) { __builtin_amdgcn_s_sleep(1); \
;     if ((++_sp & 255u) == 0u) { if (xb_ld(&(bar)[XB_TMO])) break; if (_sp > XB_SPIN_CAP) { atomicAdd(&(bar)[XB_TMO], 1u); break; } } } } while (0)
; DI void xcd_barrier(const XcdBarrier& b) {
;     ...
;     const unsigned old = xb_add(&bar[XB_XSUB(b.x)], 1u);
;     const unsigned gen = old / nloc;
;     if (old + 1u == (gen + 1u) * nloc) {
;       __builtin_amdgcn_fence(__ATOMIC_RELEASE, "agent");
;       asm volatile("s_waitcnt vmcnt(0)" ::: "memory");
;       const unsigned og = xb_add(&bar[XB_TOP], 1u);
;       const unsigned tg = og / nx;
;       if (og + 1u == (tg + 1u) * nx) xb_add(&bar[XB_TOPGEN], 1u);
;       else XB_SPIN(xb_ld(&bar[XB_TOPGEN]) == tg, bar);
.LBB0_1518:
	s_or_b64 exec, exec, s[6:7]
	v_cvt_f32_u32_e32 v3, v0
	s_waitcnt vmcnt(0)
	v_readfirstlane_b32 s4, v2
	s_add_u32 s6, s86, 0xe7c4500
	s_addc_u32 s7, s87, 0
	v_rcp_iflag_f32_e32 v3, v3
	v_add_u32_e32 v1, s4, v1
	v_add_u32_e32 v4, 1, v1
	s_mov_b64 s[8:9], -1
	v_mul_f32_e32 v2, 0x4f7ffffe, v3
	v_cvt_u32_f32_e32 v2, v2
	v_sub_u32_e32 v3, 0, v0
	v_mul_lo_u32 v3, v3, v2
	v_mul_hi_u32 v3, v2, v3
	v_add_u32_e32 v2, v2, v3
	v_mul_hi_u32 v2, v1, v2
	v_mul_lo_u32 v3, v2, v0
	v_sub_u32_e32 v1, v1, v3
	v_add_u32_e32 v5, 1, v2
	v_cmp_ge_u32_e32 vcc, v1, v0
	v_sub_u32_e32 v3, v1, v0
	s_nop 0
	v_cndmask_b32_e32 v2, v2, v5, vcc
	v_cndmask_b32_e32 v1, v1, v3, vcc
	v_add_u32_e32 v3, 1, v2
	v_cmp_ge_u32_e32 vcc, v1, v0
	s_nop 1
	v_cndmask_b32_e32 v2, v2, v3, vcc
	v_mul_lo_u32 v1, v0, v2
	v_add_u32_e32 v0, v1, v0
	v_cmp_ne_u32_e32 vcc, v4, v0
	v_mov_b32_e32 v232, v0
	v_mov_b64_e32 v[0:1], s[6:7]
	s_and_saveexec_b64 s[4:5], vcc
	s_cbranch_execz .LBB0_1530
	v_mov_b32_e32 v0, 0
	v_mov_b32_e32 v233, 0xe7c4000
	global_load_dword v1, v233, s[86:87] offset:1024 sc1
	s_mov_b64 s[12:13], 0
	s_waitcnt vmcnt(0)
	v_cmp_lt_u32_e32 vcc, v1, v232
	v_mov_b32_e32 v231, v1
	s_and_saveexec_b64 s[10:11], vcc
	s_cbranch_execz .LBB0_1529
	s_add_u32 s8, s86, 0xe7c1200
	s_addc_u32 s9, s87, 0
	s_mov_b32 s22, 1
	s_branch .LBB0_1522

; DI unsigned xb_ld(unsigned* p) { return __hip_atomic_load(p, __ATOMIC_RELAXED, __HIP_MEMORY_SCOPE_AGENT); }
; DI unsigned xb_add(unsigned* p, unsigned v) { return __hip_atomic_fetch_add(p, v, __ATOMIC_RELAXED, __HIP_MEMORY_SCOPE_AGENT); }
; #define XB_SPIN(cond, bar) do { unsigned _sp = 0; while (cond) { __builtin_amdgcn_s_sleep(1); \
;     if ((++_sp & 255u) == 0u) { if (xb_ld(&(bar)[XB_TMO])) break; if (_sp > XB_SPIN_CAP) { atomicAdd(&(bar)[XB_TMO], 1u); break; } } } } while (0)
; DI void xcd_barrier(const XcdBarrier& b) {
;     ...
;       const unsigned og = xb_add(&bar[XB_TOP], 1u);
;       const unsigned tg = og / nx;
;       if (og + 1u == (tg + 1u) * nx) xb_add(&bar[XB_TOPGEN], 1u);
;       else XB_SPIN(xb_ld(&bar[XB_TOPGEN]) == tg, bar);
.LBB0_1526:
	global_load_dword v231, v233, s[86:87] offset:1024 sc1
	s_add_i32 s22, s22, 1
	s_mov_b64 s[16:17], -1
	s_waitcnt vmcnt(3)
	v_cmp_ge_u32_e32 vcc, v231, v232
	s_orn2_b64 s[20:21], vcc, exec
	s_branch .LBB0_1521

; DI unsigned xb_add(unsigned* p, unsigned v) { return __hip_atomic_fetch_add(p, v, __ATOMIC_RELAXED, __HIP_MEMORY_SCOPE_AGENT); }
; DI void xcd_barrier(const XcdBarrier& b) {
;     ...
;       __builtin_amdgcn_fence(__ATOMIC_ACQUIRE, "agent");
;       xb_add(&bar[XB_XGEN(b.x)], 1u);
;       asm volatile("s_waitcnt vmcnt(0)" ::: "memory");
.LBB0_1532:
	s_or_b64 exec, exec, s[4:5]
	s_mov_b64 s[4:5], exec
	v_mbcnt_lo_u32_b32 v0, s4, 0
	v_mbcnt_hi_u32_b32 v0, s5, v0
	v_cmp_eq_u32_e32 vcc, 0, v0
	s_waitcnt vmcnt(3)
	s_and_saveexec_b64 s[6:7], vcc
	s_cbranch_execz .LBB0_1534
	s_bcnt1_i32_b64 s4, s[4:5]
	v_mov_b32_e32 v0, 0x2000
	v_mov_b32_e32 v1, s4
	global_atomic_add v0, v1, s[0:1] offset:1024
.LBB0_1534:
	s_or_b64 exec, exec, s[6:7]
	s_waitcnt vmcnt(3)
